# selC2 fast path (exp interleaved with next-tile score MFMAs, ping-pong score regs) + phase J/A 4-row batches + S5 table commit after u loads + NSA gate loads paired, window tile 0 fetched early + work
# speedup vs baseline: 1.0736x; 1.0054x over previous
; DI void phaseA(int wv0, PP p, unsigned char* smem) {
;     ...
;   for (int row = blockIdx.x * 8 + wv0; row < T_; row += gridDim.x * 8) {
;     const float4* xr = (const float4*)(p->x + (size_t)row * 1024);
;     float4 v[4];
;     float ss = 0.f;
; #pragma unroll
;     for (int r = 0; r < 4; ++r) {
;       v[r] = xr[lane + 64 * r];
;       ss += v[r].x * v[r].x + v[r].y * v[r].y + v[r].z * v[r].z + v[r].w * v[r].w;
;     }
;     ss = wave_sum(ss);
;     const float rinv = rsqrtf(ss * (1.f / 1024.f) + 1e-6f);
.LBB0_60:
	v_mov_b32_e32 v2, v18
	s_load_dwordx2 s[26:27], s[24:25], 0xc8
	s_lshl_b32 s0, s94, 3
	s_add_i32 s2, s89, s0
	s_cmpk_gt_i32 s2, 0x7fff
	s_cbranch_scc1 .LBB0_63
	v_and_b32_e32 v3, 0xffffffc0, v4
	v_add_u32_e32 v5, 64, v3
	v_xor_b32_e32 v3, 32, v4
	v_cmp_lt_i32_e32 vcc, v3, v5
	v_xor_b32_e32 v6, 16, v4
	s_load_dwordx4 s[4:7], s[24:25], 0x0
	v_cndmask_b32_e32 v3, v4, v3, vcc
	v_cmp_lt_i32_e32 vcc, v6, v5
	s_load_dword s3, s[90:91], 0xd8
	v_and_b32_e32 v13, 63, v2
	v_cndmask_b32_e32 v6, v4, v6, vcc
	v_lshlrev_b32_e32 v8, 2, v6
	v_xor_b32_e32 v6, 8, v4
	v_cmp_lt_i32_e32 vcc, v6, v5
	v_lshlrev_b32_e32 v14, 2, v13
	s_waitcnt lgkmcnt(0)
	s_add_u32 s0, s26, 0xb3d4100
	v_cndmask_b32_e32 v6, v4, v6, vcc
	v_lshlrev_b32_e32 v9, 2, v6
	v_xor_b32_e32 v6, 4, v4
	v_cmp_lt_i32_e32 vcc, v6, v5
	v_mov_b32_e32 v7, 0
	v_or_b32_e32 v16, 0x100, v14
	v_cndmask_b32_e32 v6, v4, v6, vcc
	v_lshlrev_b32_e32 v10, 2, v6
	v_xor_b32_e32 v6, 2, v4
	v_cmp_lt_i32_e32 vcc, v6, v5
	v_or_b32_e32 v20, 0x200, v14
	v_or_b32_e32 v22, 0x300, v14
	v_cndmask_b32_e32 v6, v4, v6, vcc
	v_lshlrev_b32_e32 v11, 2, v6
	v_xor_b32_e32 v6, 1, v4
	v_cmp_lt_i32_e32 vcc, v6, v5
	s_addc_u32 s1, s27, 0
	v_lshlrev_b32_e32 v3, 2, v3
	v_cndmask_b32_e32 v4, v4, v6, vcc
	v_lshlrev_b32_e32 v6, 4, v13
	v_lshlrev_b32_e32 v12, 2, v4
	s_lshl_b32 s8, s3, 3
	v_lshl_add_u64 v[4:5], s[6:7], 0, v[6:7]
	v_lshl_add_u64 v[6:7], s[4:5], 0, v[6:7]
	v_lshlrev_b32_e32 v13, 1, v14
	v_lshlrev_b32_e32 v14, 1, v16
	v_lshlrev_b32_e32 v15, 1, v20
	v_mov_b32_e32 v16, 0x358637bd
	s_mov_b32 s4, 0x800000
	v_lshlrev_b32_e32 v17, 1, v22
	global_load_dwordx4 v[56:59], v[4:5], off
	global_load_dwordx4 v[60:63], v[4:5], off offset:1024
	global_load_dwordx4 v[64:67], v[4:5], off offset:2048
	global_load_dwordx4 v[68:71], v[4:5], off offset:3072
	v_mov_b32_e32 v94, v13
	v_mov_b32_e32 v95, 0
	v_lshl_add_u64 v[92:93], s[0:1], 0, v[94:95]
.Lmy_A_loop:
	s_mov_b32 s5, 0
	s_mov_b32 s3, s2
	s_mov_b32 s7, 0
	s_lshl_b32 s6, s3, 12
	v_lshl_add_u64 v[72:73], v[6:7], 0, s[6:7]
	s_lshl_b32 s6, s3, 11
	v_lshl_add_u64 v[24:25], v[92:93], 0, s[6:7]
	global_load_dwordx4 v[96:99], v[72:73], off
	global_load_dwordx4 v[100:103], v[72:73], off offset:1024
	global_load_dwordx4 v[104:107], v[72:73], off offset:2048
	global_load_dwordx4 v[108:111], v[72:73], off offset:3072
	s_add_i32 s5, s5, 1
	s_add_i32 s3, s3, s8
	s_cmpk_gt_i32 s3, 0x7fff
	s_cbranch_scc1 .Lmy_A_issued
	s_lshl_b32 s6, s3, 12
	v_lshl_add_u64 v[74:75], v[6:7], 0, s[6:7]
	s_lshl_b32 s6, s3, 11
	v_lshl_add_u64 v[26:27], v[92:93], 0, s[6:7]
	global_load_dwordx4 v[112:115], v[74:75], off
	global_load_dwordx4 v[116:119], v[74:75], off offset:1024
	global_load_dwordx4 v[120:123], v[74:75], off offset:2048
	global_load_dwordx4 v[124:127], v[74:75], off offset:3072
	s_add_i32 s5, s5, 1
	s_add_i32 s3, s3, s8
	s_cmpk_gt_i32 s3, 0x7fff
	s_cbranch_scc1 .Lmy_A_issued
	s_lshl_b32 s6, s3, 12
	v_lshl_add_u64 v[76:77], v[6:7], 0, s[6:7]
	s_lshl_b32 s6, s3, 11
	v_lshl_add_u64 v[28:29], v[92:93], 0, s[6:7]
	global_load_dwordx4 v[128:131], v[76:77], off
	global_load_dwordx4 v[132:135], v[76:77], off offset:1024
	global_load_dwordx4 v[136:139], v[76:77], off offset:2048
	global_load_dwordx4 v[140:143], v[76:77], off offset:3072
	s_add_i32 s5, s5, 1
	s_add_i32 s3, s3, s8
	s_cmpk_gt_i32 s3, 0x7fff
	s_cbranch_scc1 .Lmy_A_issued
	s_lshl_b32 s6, s3, 12
	v_lshl_add_u64 v[78:79], v[6:7], 0, s[6:7]
	s_lshl_b32 s6, s3, 11
	v_lshl_add_u64 v[30:31], v[92:93], 0, s[6:7]
	global_load_dwordx4 v[144:147], v[78:79], off
	global_load_dwordx4 v[148:151], v[78:79], off offset:1024
	global_load_dwordx4 v[152:155], v[78:79], off offset:2048
	global_load_dwordx4 v[156:159], v[78:79], off offset:3072
	s_add_i32 s5, s5, 1
	s_add_i32 s3, s3, s8
.Lmy_A_issued:
	s_waitcnt vmcnt(0)
	v_mov_b32_e32 v46, v97
	v_mov_b32_e32 v47, v101
	v_mov_b32_e32 v44, v96
	v_mov_b32_e32 v45, v100
	v_mov_b32_e32 v54, v105
	v_mov_b32_e32 v55, v109
	v_pk_mul_f32 v[46:47], v[46:47], v[46:47]
	v_mov_b32_e32 v40, v98
	v_mov_b32_e32 v41, v102
	v_mov_b32_e32 v52, v104
	v_mov_b32_e32 v53, v108
	v_pk_mul_f32 v[54:55], v[54:55], v[54:55]
	v_pk_fma_f32 v[44:45], v[44:45], v[44:45], v[46:47]
	v_mov_b32_e32 v42, v99
	v_mov_b32_e32 v43, v103
	v_mov_b32_e32 v48, v106
	v_mov_b32_e32 v49, v110
	v_pk_fma_f32 v[46:47], v[52:53], v[52:53], v[54:55]
	v_pk_fma_f32 v[40:41], v[40:41], v[40:41], v[44:45]
	v_mov_b32_e32 v50, v107
	v_mov_b32_e32 v51, v111
	v_pk_fma_f32 v[44:45], v[48:49], v[48:49], v[46:47]
	v_pk_fma_f32 v[40:41], v[42:43], v[42:43], v[40:41]
	v_pk_fma_f32 v[42:43], v[50:51], v[50:51], v[44:45]
	v_add_f32_e32 v80, v40, v41
	v_add_f32_e32 v80, v80, v42
	v_add_f32_e32 v80, v80, v43
	v_mov_b32_e32 v46, v113
	v_mov_b32_e32 v47, v117
	v_mov_b32_e32 v44, v112
	v_mov_b32_e32 v45, v116
	v_mov_b32_e32 v54, v121
	v_mov_b32_e32 v55, v125
	v_pk_mul_f32 v[46:47], v[46:47], v[46:47]
	v_mov_b32_e32 v40, v114
	v_mov_b32_e32 v41, v118
	v_mov_b32_e32 v52, v120
	v_mov_b32_e32 v53, v124
	v_pk_mul_f32 v[54:55], v[54:55], v[54:55]
	v_pk_fma_f32 v[44:45], v[44:45], v[44:45], v[46:47]
	v_mov_b32_e32 v42, v115
	v_mov_b32_e32 v43, v119
	v_mov_b32_e32 v48, v122
	v_mov_b32_e32 v49, v126
	v_pk_fma_f32 v[46:47], v[52:53], v[52:53], v[54:55]
	v_pk_fma_f32 v[40:41], v[40:41], v[40:41], v[44:45]
	v_mov_b32_e32 v50, v123
	v_mov_b32_e32 v51, v127
	v_pk_fma_f32 v[44:45], v[48:49], v[48:49], v[46:47]
	v_pk_fma_f32 v[40:41], v[42:43], v[42:43], v[40:41]
	v_pk_fma_f32 v[42:43], v[50:51], v[50:51], v[44:45]
	v_add_f32_e32 v81, v40, v41
	v_add_f32_e32 v81, v81, v42
	v_add_f32_e32 v81, v81, v43
	v_mov_b32_e32 v46, v129
	v_mov_b32_e32 v47, v133
	v_mov_b32_e32 v44, v128
	v_mov_b32_e32 v45, v132
; DI void phaseA(int wv0, PP p, unsigned char* smem) {
;     ...
; #pragma unroll
;     for (int r = 0; r < 4; ++r) {
;       v[r] = xr[lane + 64 * r];
;       ss += v[r].x * v[r].x + v[r].y * v[r].y + v[r].z * v[r].z + v[r].w * v[r].w;
;     }
;     ss = wave_sum(ss);
;     const float rinv = rsqrtf(ss * (1.f / 1024.f) + 1e-6f);
; #pragma unroll
;     for (int r = 0; r < 4; ++r) {
;       const float4 g = ((const float4*)p->g1)[lane + 64 * r];
;       uint2 o;
;       o.x = pk2(v[r].x * rinv * g.x, v[r].y * rinv * g.y);
;       o.y = pk2(v[r].z * rinv * g.z, v[r].w * rinv * g.w);
;       *(uint2*)(HN + (size_t)row * 1024 + (lane + 64 * r) * 4) = o;
	v_mov_b32_e32 v54, v137
	v_mov_b32_e32 v55, v141
	v_pk_mul_f32 v[46:47], v[46:47], v[46:47]
	v_mov_b32_e32 v40, v130
	v_mov_b32_e32 v41, v134
	v_mov_b32_e32 v52, v136
	v_mov_b32_e32 v53, v140
	v_pk_mul_f32 v[54:55], v[54:55], v[54:55]
	v_pk_fma_f32 v[44:45], v[44:45], v[44:45], v[46:47]
	v_mov_b32_e32 v42, v131
	v_mov_b32_e32 v43, v135
	v_mov_b32_e32 v48, v138
	v_mov_b32_e32 v49, v142
	v_pk_fma_f32 v[46:47], v[52:53], v[52:53], v[54:55]
	v_pk_fma_f32 v[40:41], v[40:41], v[40:41], v[44:45]
	v_mov_b32_e32 v50, v139
	v_mov_b32_e32 v51, v143
	v_pk_fma_f32 v[44:45], v[48:49], v[48:49], v[46:47]
	v_pk_fma_f32 v[40:41], v[42:43], v[42:43], v[40:41]
	v_pk_fma_f32 v[42:43], v[50:51], v[50:51], v[44:45]
	v_add_f32_e32 v82, v40, v41
	v_add_f32_e32 v82, v82, v42
	v_add_f32_e32 v82, v82, v43
	v_mov_b32_e32 v46, v145
	v_mov_b32_e32 v47, v149
	v_mov_b32_e32 v44, v144
	v_mov_b32_e32 v45, v148
	v_mov_b32_e32 v54, v153
	v_mov_b32_e32 v55, v157
	v_pk_mul_f32 v[46:47], v[46:47], v[46:47]
	v_mov_b32_e32 v40, v146
	v_mov_b32_e32 v41, v150
	v_mov_b32_e32 v52, v152
	v_mov_b32_e32 v53, v156
	v_pk_mul_f32 v[54:55], v[54:55], v[54:55]
	v_pk_fma_f32 v[44:45], v[44:45], v[44:45], v[46:47]
	v_mov_b32_e32 v42, v147
	v_mov_b32_e32 v43, v151
	v_mov_b32_e32 v48, v154
	v_mov_b32_e32 v49, v158
	v_pk_fma_f32 v[46:47], v[52:53], v[52:53], v[54:55]
	v_pk_fma_f32 v[40:41], v[40:41], v[40:41], v[44:45]
	v_mov_b32_e32 v50, v155
	v_mov_b32_e32 v51, v159
	v_pk_fma_f32 v[44:45], v[48:49], v[48:49], v[46:47]
	v_pk_fma_f32 v[40:41], v[42:43], v[42:43], v[40:41]
	v_pk_fma_f32 v[42:43], v[50:51], v[50:51], v[44:45]
	v_add_f32_e32 v83, v40, v41
	v_add_f32_e32 v83, v83, v42
	v_add_f32_e32 v83, v83, v43
	ds_bpermute_b32 v32, v3, v80
	ds_bpermute_b32 v33, v3, v81
	ds_bpermute_b32 v34, v3, v82
	ds_bpermute_b32 v35, v3, v83
	s_waitcnt lgkmcnt(0)
	v_add_f32_e32 v80, v80, v32
	v_add_f32_e32 v81, v81, v33
	v_add_f32_e32 v82, v82, v34
	v_add_f32_e32 v83, v83, v35
	ds_bpermute_b32 v32, v8, v80
	ds_bpermute_b32 v33, v8, v81
	ds_bpermute_b32 v34, v8, v82
	ds_bpermute_b32 v35, v8, v83
	s_waitcnt lgkmcnt(0)
	v_add_f32_e32 v80, v80, v32
	v_add_f32_e32 v81, v81, v33
	v_add_f32_e32 v82, v82, v34
	v_add_f32_e32 v83, v83, v35
	ds_bpermute_b32 v32, v9, v80
	ds_bpermute_b32 v33, v9, v81
	ds_bpermute_b32 v34, v9, v82
	ds_bpermute_b32 v35, v9, v83
	s_waitcnt lgkmcnt(0)
	v_add_f32_e32 v80, v80, v32
	v_add_f32_e32 v81, v81, v33
	v_add_f32_e32 v82, v82, v34
	v_add_f32_e32 v83, v83, v35
	ds_bpermute_b32 v32, v10, v80
	ds_bpermute_b32 v33, v10, v81
	ds_bpermute_b32 v34, v10, v82
	ds_bpermute_b32 v35, v10, v83
	s_waitcnt lgkmcnt(0)
	v_add_f32_e32 v80, v80, v32
	v_add_f32_e32 v81, v81, v33
	v_add_f32_e32 v82, v82, v34
	v_add_f32_e32 v83, v83, v35
	ds_bpermute_b32 v32, v11, v80
	ds_bpermute_b32 v33, v11, v81
	ds_bpermute_b32 v34, v11, v82
	ds_bpermute_b32 v35, v11, v83
	s_waitcnt lgkmcnt(0)
	v_add_f32_e32 v80, v80, v32
	v_add_f32_e32 v81, v81, v33
	v_add_f32_e32 v82, v82, v34
	v_add_f32_e32 v83, v83, v35
	ds_bpermute_b32 v32, v12, v80
	ds_bpermute_b32 v33, v12, v81
	ds_bpermute_b32 v34, v12, v82
	ds_bpermute_b32 v35, v12, v83
	s_waitcnt lgkmcnt(0)
	v_add_f32_e32 v80, v80, v32
	v_add_f32_e32 v81, v81, v33
	v_add_f32_e32 v82, v82, v34
	v_add_f32_e32 v83, v83, v35
	v_fmamk_f32 v80, v80, 0x3a800000, v16
	v_fmamk_f32 v81, v81, 0x3a800000, v16
	v_fmamk_f32 v82, v82, 0x3a800000, v16
	v_fmamk_f32 v83, v83, 0x3a800000, v16
	v_mul_f32_e32 v32, 0x4b800000, v80
	v_cmp_gt_f32_e64 s[6:7], s4, v80
	s_nop 1
	v_cndmask_b32_e64 v80, v80, v32, s[6:7]
	v_rsq_f32_e32 v80, v80
	s_nop 0
	v_mul_f32_e32 v32, 0x45800000, v80
	v_cndmask_b32_e64 v84, v80, v32, s[6:7]
	v_mul_f32_e32 v32, 0x4b800000, v81
	v_cmp_gt_f32_e64 s[6:7], s4, v81
	s_nop 1
	v_cndmask_b32_e64 v81, v81, v32, s[6:7]
	v_rsq_f32_e32 v81, v81
	s_nop 0
	v_mul_f32_e32 v32, 0x45800000, v81
	v_cndmask_b32_e64 v86, v81, v32, s[6:7]
	v_mul_f32_e32 v32, 0x4b800000, v82
	v_cmp_gt_f32_e64 s[6:7], s4, v82
	s_nop 1
	v_cndmask_b32_e64 v82, v82, v32, s[6:7]
	v_rsq_f32_e32 v82, v82
	s_nop 0
	v_mul_f32_e32 v32, 0x45800000, v82
	v_cndmask_b32_e64 v88, v82, v32, s[6:7]
	v_mul_f32_e32 v32, 0x4b800000, v83
	v_cmp_gt_f32_e64 s[6:7], s4, v83
	s_nop 1
	v_cndmask_b32_e64 v83, v83, v32, s[6:7]
	v_rsq_f32_e32 v83, v83
	s_nop 0
	v_mul_f32_e32 v32, 0x45800000, v83
	v_cndmask_b32_e64 v90, v83, v32, s[6:7]
	v_pk_mul_f32 v[20:21], v[96:97], v[84:85] op_sel_hi:[1,0]
	v_pk_mul_f32 v[22:23], v[98:99], v[84:85] op_sel_hi:[1,0]
	v_pk_mul_f32 v[20:21], v[56:57], v[20:21]
	v_pk_mul_f32 v[22:23], v[58:59], v[22:23]
	v_cvt_pk_bf16_f32 v96, v20, v21
	v_cvt_pk_bf16_f32 v97, v22, v23
	global_store_dwordx2 v[24:25], v[96:97], off
	v_pk_mul_f32 v[20:21], v[100:101], v[84:85] op_sel_hi:[1,0]
	v_pk_mul_f32 v[22:23], v[102:103], v[84:85] op_sel_hi:[1,0]
	v_pk_mul_f32 v[20:21], v[60:61], v[20:21]
	v_pk_mul_f32 v[22:23], v[62:63], v[22:23]
	v_cvt_pk_bf16_f32 v100, v20, v21
	v_cvt_pk_bf16_f32 v101, v22, v23
	global_store_dwordx2 v[24:25], v[100:101], off offset:512
	v_pk_mul_f32 v[20:21], v[104:105], v[84:85] op_sel_hi:[1,0]
	v_pk_mul_f32 v[22:23], v[106:107], v[84:85] op_sel_hi:[1,0]
	v_pk_mul_f32 v[20:21], v[64:65], v[20:21]
	v_pk_mul_f32 v[22:23], v[66:67], v[22:23]
	v_cvt_pk_bf16_f32 v104, v20, v21
	v_cvt_pk_bf16_f32 v105, v22, v23
	global_store_dwordx2 v[24:25], v[104:105], off offset:1024
	v_pk_mul_f32 v[20:21], v[108:109], v[84:85] op_sel_hi:[1,0]
	v_pk_mul_f32 v[22:23], v[110:111], v[84:85] op_sel_hi:[1,0]
	v_pk_mul_f32 v[20:21], v[68:69], v[20:21]
	v_pk_mul_f32 v[22:23], v[70:71], v[22:23]
	v_cvt_pk_bf16_f32 v108, v20, v21
	v_cvt_pk_bf16_f32 v109, v22, v23
	global_store_dwordx2 v[24:25], v[108:109], off offset:1536
	s_cmp_gt_u32 s5, 1
	s_cbranch_scc0 .Lmy_A_stored
; DI void phaseA(int wv0, PP p, unsigned char* smem) {
;     ...
; #pragma unroll
;     for (int r = 0; r < 4; ++r) {
;       const float4 g = ((const float4*)p->g1)[lane + 64 * r];
;       uint2 o;
;       o.x = pk2(v[r].x * rinv * g.x, v[r].y * rinv * g.y);
;       o.y = pk2(v[r].z * rinv * g.z, v[r].w * rinv * g.w);
;       *(uint2*)(HN + (size_t)row * 1024 + (lane + 64 * r) * 4) = o;
;     }
	v_pk_mul_f32 v[20:21], v[112:113], v[86:87] op_sel_hi:[1,0]
	v_pk_mul_f32 v[22:23], v[114:115], v[86:87] op_sel_hi:[1,0]
	v_pk_mul_f32 v[20:21], v[56:57], v[20:21]
	v_pk_mul_f32 v[22:23], v[58:59], v[22:23]
	v_cvt_pk_bf16_f32 v112, v20, v21
	v_cvt_pk_bf16_f32 v113, v22, v23
	global_store_dwordx2 v[26:27], v[112:113], off
	v_pk_mul_f32 v[20:21], v[116:117], v[86:87] op_sel_hi:[1,0]
	v_pk_mul_f32 v[22:23], v[118:119], v[86:87] op_sel_hi:[1,0]
	v_pk_mul_f32 v[20:21], v[60:61], v[20:21]
	v_pk_mul_f32 v[22:23], v[62:63], v[22:23]
	v_cvt_pk_bf16_f32 v116, v20, v21
	v_cvt_pk_bf16_f32 v117, v22, v23
	global_store_dwordx2 v[26:27], v[116:117], off offset:512
	v_pk_mul_f32 v[20:21], v[120:121], v[86:87] op_sel_hi:[1,0]
	v_pk_mul_f32 v[22:23], v[122:123], v[86:87] op_sel_hi:[1,0]
	v_pk_mul_f32 v[20:21], v[64:65], v[20:21]
	v_pk_mul_f32 v[22:23], v[66:67], v[22:23]
	v_cvt_pk_bf16_f32 v120, v20, v21
	v_cvt_pk_bf16_f32 v121, v22, v23
	global_store_dwordx2 v[26:27], v[120:121], off offset:1024
	v_pk_mul_f32 v[20:21], v[124:125], v[86:87] op_sel_hi:[1,0]
	v_pk_mul_f32 v[22:23], v[126:127], v[86:87] op_sel_hi:[1,0]
	v_pk_mul_f32 v[20:21], v[68:69], v[20:21]
	v_pk_mul_f32 v[22:23], v[70:71], v[22:23]
	v_cvt_pk_bf16_f32 v124, v20, v21
	v_cvt_pk_bf16_f32 v125, v22, v23
	global_store_dwordx2 v[26:27], v[124:125], off offset:1536
	s_cmp_gt_u32 s5, 2
	s_cbranch_scc0 .Lmy_A_stored
	v_pk_mul_f32 v[20:21], v[128:129], v[88:89] op_sel_hi:[1,0]
	v_pk_mul_f32 v[22:23], v[130:131], v[88:89] op_sel_hi:[1,0]
	v_pk_mul_f32 v[20:21], v[56:57], v[20:21]
	v_pk_mul_f32 v[22:23], v[58:59], v[22:23]
	v_cvt_pk_bf16_f32 v128, v20, v21
	v_cvt_pk_bf16_f32 v129, v22, v23
	global_store_dwordx2 v[28:29], v[128:129], off
	v_pk_mul_f32 v[20:21], v[132:133], v[88:89] op_sel_hi:[1,0]
	v_pk_mul_f32 v[22:23], v[134:135], v[88:89] op_sel_hi:[1,0]
	v_pk_mul_f32 v[20:21], v[60:61], v[20:21]
	v_pk_mul_f32 v[22:23], v[62:63], v[22:23]
	v_cvt_pk_bf16_f32 v132, v20, v21
	v_cvt_pk_bf16_f32 v133, v22, v23
	global_store_dwordx2 v[28:29], v[132:133], off offset:512
	v_pk_mul_f32 v[20:21], v[136:137], v[88:89] op_sel_hi:[1,0]
	v_pk_mul_f32 v[22:23], v[138:139], v[88:89] op_sel_hi:[1,0]
	v_pk_mul_f32 v[20:21], v[64:65], v[20:21]
	v_pk_mul_f32 v[22:23], v[66:67], v[22:23]
	v_cvt_pk_bf16_f32 v136, v20, v21
	v_cvt_pk_bf16_f32 v137, v22, v23
	global_store_dwordx2 v[28:29], v[136:137], off offset:1024
	v_pk_mul_f32 v[20:21], v[140:141], v[88:89] op_sel_hi:[1,0]
	v_pk_mul_f32 v[22:23], v[142:143], v[88:89] op_sel_hi:[1,0]
	v_pk_mul_f32 v[20:21], v[68:69], v[20:21]
	v_pk_mul_f32 v[22:23], v[70:71], v[22:23]
	v_cvt_pk_bf16_f32 v140, v20, v21
	v_cvt_pk_bf16_f32 v141, v22, v23
	global_store_dwordx2 v[28:29], v[140:141], off offset:1536
	s_cmp_gt_u32 s5, 3
	s_cbranch_scc0 .Lmy_A_stored
	v_pk_mul_f32 v[20:21], v[144:145], v[90:91] op_sel_hi:[1,0]
	v_pk_mul_f32 v[22:23], v[146:147], v[90:91] op_sel_hi:[1,0]
	v_pk_mul_f32 v[20:21], v[56:57], v[20:21]
	v_pk_mul_f32 v[22:23], v[58:59], v[22:23]
	v_cvt_pk_bf16_f32 v144, v20, v21
	v_cvt_pk_bf16_f32 v145, v22, v23
	global_store_dwordx2 v[30:31], v[144:145], off
	v_pk_mul_f32 v[20:21], v[148:149], v[90:91] op_sel_hi:[1,0]
	v_pk_mul_f32 v[22:23], v[150:151], v[90:91] op_sel_hi:[1,0]
	v_pk_mul_f32 v[20:21], v[60:61], v[20:21]
	v_pk_mul_f32 v[22:23], v[62:63], v[22:23]
	v_cvt_pk_bf16_f32 v148, v20, v21
	v_cvt_pk_bf16_f32 v149, v22, v23
	global_store_dwordx2 v[30:31], v[148:149], off offset:512
	v_pk_mul_f32 v[20:21], v[152:153], v[90:91] op_sel_hi:[1,0]
	v_pk_mul_f32 v[22:23], v[154:155], v[90:91] op_sel_hi:[1,0]
	v_pk_mul_f32 v[20:21], v[64:65], v[20:21]
	v_pk_mul_f32 v[22:23], v[66:67], v[22:23]
	v_cvt_pk_bf16_f32 v152, v20, v21
	v_cvt_pk_bf16_f32 v153, v22, v23
	global_store_dwordx2 v[30:31], v[152:153], off offset:1024
	v_pk_mul_f32 v[20:21], v[156:157], v[90:91] op_sel_hi:[1,0]
	v_pk_mul_f32 v[22:23], v[158:159], v[90:91] op_sel_hi:[1,0]
	v_pk_mul_f32 v[20:21], v[68:69], v[20:21]
	v_pk_mul_f32 v[22:23], v[70:71], v[22:23]
	v_cvt_pk_bf16_f32 v156, v20, v21
	v_cvt_pk_bf16_f32 v157, v22, v23
	global_store_dwordx2 v[30:31], v[156:157], off offset:1536
.Lmy_A_stored:
	s_mov_b32 s2, s3
	s_cmpk_gt_i32 s2, 0x7fff
	s_cbranch_scc0 .Lmy_A_loop

; template <bool OUT>
; DI void s5_item(int wv0, PP p, int item, unsigned char* smem) {
;   const int tid = my_tid(wv0), lane = tid & 63, fr = lane & 15, fq = lane >> 4;
;   const int b = item >> 9, g = (item >> 4) & 31, c8 = item & 15, ch = c8 * 8 + wv0;
;   u16* sBb = (u16*)smem;
;   u16* sCm = sBb + 128 * 16;
;   float* sBU = (float*)(smem + 8192) + wv0 * (16 * 132);
;   u16* sH = (u16*)(smem + 8192 + 8 * 16 * 132 * 4) + wv0 * (16 * 136);
;   *(uint4*)(smem + tid * 16) = *(const uint4*)(p->ws + OFF_S5T + (size_t)g * 8192 + tid * 16);
;   const float2 lb = ((const float2*)(p->ws + OFF_S5L))[g * 64 + lane];
;   const float lbr = lb.x, lbi = lb.y;
;   float2* HL = (float2*)(p->ws + OFF_HLOC) + ((size_t)(b * 128 + ch) * 32 + g) * 64 + lane;
;   float hr = 0.f, hi = 0.f;
;   if (OUT) { const float2 h0 = *HL; hr = h0.x; hi = h0.y; }
;   const u16* U = (const u16*)(p->ws + OFF_U) + ((size_t)(b * S_ + ch * 64)) * 512 + g * 16;
;   u16* YS = (u16*)(p->ws + OFF_YS) + ((size_t)(b * S_ + ch * 64)) * 512 + g * 16;
;   const float dk = p->dsk[g * 16 + fr];
;   const bf16x8 zero8 = {0, 0, 0, 0, 0, 0, 0, 0};
;   bf16x8 uall[4];
;   u16 usk[4][4];
; #pragma unroll
;   for (int sub = 0; sub < 4; ++sub) {
;     uall[sub] = fq < 2 ? *(const bf16x8*)(U + (size_t)(sub * 16 + fr) * 512 + 8 * fq) : zero8;
.LBB0_414:
	s_cmpk_lt_i32 s64, 0x880
	s_mov_b64 s[2:3], -1
	s_cbranch_scc0 .LBB0_458
	s_cmpk_gt_i32 s64, 0x7f
	s_cbranch_scc0 .LBB0_449
	v_mov_b32_e32 v52, v144
	s_load_dwordx2 s[42:43], s[6:7], 0xc8
	s_add_i32 s2, s64, 0xffffff80
	s_lshr_b32 s66, s2, 9
	s_bfe_u32 s65, s2, 0x50004
	s_lshl_b32 s2, s2, 3
	s_and_b32 s67, s2, 0x78
	s_add_i32 s67, s67, s89
	s_lshl_b32 s2, s65, 13
	s_waitcnt lgkmcnt(0)
	s_add_u32 s2, s42, s2
	v_lshlrev_b32_e32 v4, 4, v52
	v_and_b32_e32 v49, 63, v52
	s_addc_u32 s3, s43, 0
	v_ashrrev_i32_e32 v5, 31, v4
	v_lshl_add_u64 v[0:1], s[2:3], 0, v[4:5]
	v_lshlrev_b32_e32 v48, 3, v49
	v_add_co_u32_e32 v0, vcc, s59, v0
	v_lshl_or_b32 v128, s65, 9, v48
	s_nop 0
	v_addc_co_u32_e32 v1, vcc, 0, v1, vcc
	v_lshl_add_u64 v[6:7], s[42:43], 0, v[128:129]
	v_add_co_u32_e32 v6, vcc, s60, v6
	global_load_dwordx4 v[200:203], v[0:1], off offset:256
	s_nop 0
	v_addc_co_u32_e32 v7, vcc, 0, v7, vcc
	global_load_dwordx2 v[50:51], v[6:7], off offset:256
	s_lshl_b32 s14, s66, 13
	s_lshl_b32 s44, s67, 6
	s_add_i32 s14, s44, s14
	s_lshl_b64 s[44:45], s[14:15], 10
	s_add_u32 s14, s42, s44
	s_addc_u32 s45, s43, s45
	s_lshl_b32 s44, s65, 5
	s_add_u32 s44, s14, s44
	v_and_b32_e32 v53, 15, v52
	v_and_b32_e32 v128, 48, v52
	s_addc_u32 s45, s45, 0
	v_add_u32_e32 v204, 32, v4
	v_lshlrev_b32_e32 v4, 9, v53
	v_lshl_add_u64 v[6:7], s[44:45], 0, v[128:129]
	v_mov_b32_e32 v28, 0
	v_mov_b32_e32 v44, 0
	v_mov_b32_e32 v45, 0
	v_mov_b32_e32 v46, 0
	v_cmp_gt_u32_e64 s[2:3], 32, v49
	v_lshlrev_b32_e32 v4, 1, v4
	v_lshl_add_u64 v[6:7], v[6:7], 0, s[16:17]
	v_mov_b32_e32 v47, 0
	s_and_saveexec_b64 s[44:45], s[2:3]
	s_cbranch_execz .LBB0_418
	v_mov_b32_e32 v5, v129
	v_lshl_add_u64 v[0:1], v[6:7], 0, v[4:5]
	global_load_dwordx4 v[44:47], v[0:1], off

; DI f32x4 mfma16(bf16x8 a, bf16x8 b, f32x4 c) { return __builtin_amdgcn_mfma_f32_16x16x32_bf16(a, b, c, 0, 0, 0); }
; template <bool OUT>
; DI void s5_item(int wv0, PP p, int item, unsigned char* smem) {
;     ...
;   __syncthreads();
;   bf16x8 bb[8], cf[4];
; #pragma unroll
;   for (int nt = 0; nt < 8; ++nt) bb[nt] = fq < 2 ? *(const bf16x8*)(sBb + (16 * nt + fr) * 16 + 8 * fq) : zero8;
;   if (OUT) {
; #pragma unroll
;     for (int ks = 0; ks < 4; ++ks) cf[ks] = *(const bf16x8*)(sCm + fr * 128 + 32 * ks + 8 * fq);
;   }
; #pragma unroll
;   for (int sub = 0; sub < 4; ++sub) {
;     const bf16x8 ua = uall[sub];
; #pragma unroll
;     for (int nt = 0; nt < 8; ++nt) {
;       const f32x4 a = mfma16(ua, bb[nt], f32x4{0.f, 0.f, 0.f, 0.f});
; #pragma unroll
;       for (int j = 0; j < 4; ++j) sBU[(4 * fq + j) * 132 + 16 * nt + fr] = a[j];
;     }
;     __syncthreads();
.LBB0_424:
	s_or_b64 exec, exec, s[44:45]
	v_lshl_add_u32 v5, v53, 5, 32
	v_mov_b32_e32 v4, 0
	v_add_u32_e32 v54, v5, v128
	v_mov_b32_e32 v8, 0
	v_mov_b32_e32 v9, 0
	v_mov_b32_e32 v10, 0
	v_mov_b32_e32 v11, 0
	s_waitcnt vmcnt(4)
	ds_write_b128 v204, v[200:203]
	s_waitcnt lgkmcnt(0)
	s_barrier
	s_and_saveexec_b64 s[44:45], s[2:3]
	ds_read_b128 v[8:11], v54
	s_or_b64 exec, exec, s[44:45]
	v_mov_b32_e32 v5, 0
	v_mov_b32_e32 v6, 0
	v_mov_b32_e32 v7, 0
	s_and_saveexec_b64 s[44:45], s[2:3]
	ds_read_b128 v[4:7], v54 offset:512
	s_or_b64 exec, exec, s[44:45]
	v_mov_b32_e32 v16, 0
	v_mov_b32_e32 v20, 0
	v_mov_b32_e32 v21, 0
	v_mov_b32_e32 v22, 0
	v_mov_b32_e32 v23, 0
	s_and_saveexec_b64 s[44:45], s[2:3]
	ds_read_b128 v[20:23], v54 offset:1024
	s_or_b64 exec, exec, s[44:45]
	v_mov_b32_e32 v17, 0
	v_mov_b32_e32 v18, 0
	v_mov_b32_e32 v19, 0
	s_and_saveexec_b64 s[44:45], s[2:3]
	ds_read_b128 v[16:19], v54 offset:1536
	s_or_b64 exec, exec, s[44:45]
	v_mov_b32_e32 v24, 0
	v_mov_b32_e32 v32, 0
	v_mov_b32_e32 v33, 0
	v_mov_b32_e32 v34, 0
	v_mov_b32_e32 v35, 0
	s_and_saveexec_b64 s[44:45], s[2:3]
	ds_read_b128 v[32:35], v54 offset:2048
	s_or_b64 exec, exec, s[44:45]
	v_mov_b32_e32 v25, 0
	v_mov_b32_e32 v26, 0
	v_mov_b32_e32 v27, 0
	s_and_saveexec_b64 s[44:45], s[2:3]
	ds_read_b128 v[24:27], v54 offset:2560
	s_or_b64 exec, exec, s[44:45]
	v_mov_b32_e32 v36, 0
	v_mov_b32_e32 v40, 0
	v_mov_b32_e32 v41, 0
	v_mov_b32_e32 v42, 0
	v_mov_b32_e32 v43, 0
	s_and_saveexec_b64 s[44:45], s[2:3]
	ds_read_b128 v[40:43], v54 offset:3072
	s_or_b64 exec, exec, s[44:45]
	s_mov_b32 s14, 0
	v_mov_b32_e32 v37, 0
	v_mov_b32_e32 v38, 0
	v_mov_b32_e32 v39, 0
	s_and_saveexec_b64 s[44:45], s[2:3]
	ds_read_b128 v[36:39], v54 offset:3584
	s_or_b64 exec, exec, s[44:45]
	s_waitcnt vmcnt(0) lgkmcnt(0)
	v_mfma_f32_16x16x32_bf16 v[54:57], v[44:47], v[8:11], 0
	v_bfe_u32 v52, v52, 4, 2
	v_lshlrev_b32_e32 v53, 2, v53
	v_mul_u32_u24_e32 v52, 0x840, v52
	v_mfma_f32_16x16x32_bf16 v[58:61], v[44:47], v[4:7], 0
	v_add3_u32 v52, s0, v53, v52
	v_add_u32_e32 v53, 0x2000, v52
	v_lshl_add_u32 v49, v49, 2, s58
	v_mfma_f32_16x16x32_bf16 v[62:65], v[44:47], v[20:23], 0
	v_mfma_f32_16x16x32_bf16 v[66:69], v[44:47], v[16:19], 0
	s_nop 2
	ds_write2_b32 v53, v54, v58 offset1:16
	v_add_u32_e32 v54, 0x2400, v52
	ds_write2_b32 v53, v55, v59 offset0:132 offset1:148
	ds_write2_b32 v54, v56, v60 offset0:8 offset1:24
	v_mfma_f32_16x16x32_bf16 v[70:73], v[44:47], v[32:35], 0
	ds_write2_b32 v54, v57, v61 offset0:140 offset1:156
	ds_write2_b32 v53, v62, v66 offset0:32 offset1:48
	ds_write2_b32 v53, v63, v67 offset0:164 offset1:180
	v_mov_b32_e32 v52, 0
	v_mfma_f32_16x16x32_bf16 v[56:59], v[44:47], v[24:27], 0
	ds_write2_b32 v54, v64, v68 offset0:40 offset1:56
	ds_write2_b32 v54, v65, v69 offset0:172 offset1:188
	s_nop 5
	ds_write2_b32 v53, v70, v56 offset0:64 offset1:80
	ds_write2_b32 v53, v71, v57 offset0:196 offset1:212
	ds_write2_b32 v54, v72, v58 offset0:72 offset1:88
	ds_write2_b32 v54, v73, v59 offset0:204 offset1:220
	v_mfma_f32_16x16x32_bf16 v[60:63], v[44:47], v[40:43], 0
	v_mfma_f32_16x16x32_bf16 v[44:47], v[44:47], v[36:39], 0
	s_nop 7
	ds_write2_b32 v53, v60, v44 offset0:96 offset1:112
	ds_write2_b32 v53, v61, v45 offset0:228 offset1:244
	ds_write2_b32 v54, v62, v46 offset0:104 offset1:120
	ds_write2_b32 v54, v63, v47 offset0:236 offset1:252
	v_pk_mov_b32 v[44:45], v[50:51], v[50:51] op_sel:[1,0]
	v_mov_b32_e32 v46, 0
	s_waitcnt lgkmcnt(0)
	s_barrier

; DI void nsa_item(int wv0, PP p, int item, unsigned char* smem) {
;   const int tid = my_tid(wv0), lane = tid & 63, wv = wv0 & 3, hp = wv0 >> 2, l15 = lane & 15, lg = lane >> 4;
;   const int i = 127 - (item >> 3), bg = item & 7, b = bg >> 1, g = bg & 1;
;   u16* sK = (u16*)smem;
;   u16* sV = sK + 64 * 72;
;   float* sImp0 = (float*)(smem + 55296);
;   float* sImp = sImp0 + hp * (64 * 132);
;   u64* sUni = (u64*)(smem + 55296 + 2 * 64 * 132 * 4);
;   u64* sSel = sUni + 16;
;   const int t0 = i * 64, qloc = 16 * wv + l15, tq = t0 + qloc;
;   const unsigned tokq = (unsigned)(b * S_ + tq);
;   const float* NGb = (const float*)(p->ws + OFF_NG);
;   const unsigned ngoff = tokq * 24 + g * 12 + hp * 6;
;   float* ACCb = p->out;
;   const unsigned aoff = tokq * 512 + g * 256 + hp * 128 + 4 * lg;
;   const unsigned qoff = tokq * 512 + g * 256 + hp * 128 + lg * 8;
;   const int lrow = tid >> 3, lpart = tid & 7;
;   const unsigned koff = (lrow * 64 + lpart * 8) * 2, voffc = (lrow * 512 + lpart * 8) * 2, voffs = (lrow * S_ + lpart * 8) * 2;
; DI void phaseE(int wv0, PP p, unsigned char* smem, int cidx) {
;   __shared__ int s_item;
;   int* ctr = (int*)(p->ws + OFF_CTR) + cidx;
;   for (;;) {
;     __syncthreads();
;     if (my_tid(wv0) == 0) s_item = atomicAdd(ctr, 1);
.LBB0_722:
	v_writelane_b32 v247, s48, 7
	s_mul_i32 s0, s89, 0x2100
	s_mul_i32 s1, s89, 0x1100
	v_writelane_b32 v247, s49, 8
	v_writelane_b32 v247, s94, 9
	v_and_b32_e32 v1, 0xffffffc0, v2
	v_readlane_b32 s4, v247, 5
	v_readlane_b32 s5, v247, 6
	s_load_dwordx2 s[2:3], s[4:5], 0xc8
	v_xor_b32_e32 v0, 16, v2
	v_add_u32_e32 v1, 64, v1
	v_cmp_lt_i32_e32 vcc, v0, v1
	s_mov_b32 s71, 0x20000
	s_waitcnt lgkmcnt(0)
	s_add_u32 s6, s2, 0x1fd0000
	s_addc_u32 s7, s3, 0
	v_writelane_b32 v247, s6, 10
	v_cndmask_b32_e32 v0, v2, v0, vcc
	v_lshlrev_b32_e32 v144, 2, v0
	v_writelane_b32 v247, s7, 11
	s_add_u32 s6, s4, 0xb0
	s_addc_u32 s7, s5, 0
	v_writelane_b32 v247, s6, 12
	v_xor_b32_e32 v0, 32, v2
	v_cmp_lt_i32_e32 vcc, v0, v1
	v_writelane_b32 v247, s7, 13
	s_add_u32 s6, s2, 0x1740000
	s_addc_u32 s7, s3, 0
	v_writelane_b32 v247, s6, 14
	v_cndmask_b32_e32 v0, v2, v0, vcc
	v_lshlrev_b32_e32 v145, 2, v0
	v_writelane_b32 v247, s7, 15
	s_add_u32 s6, s4, 0xa8
	s_addc_u32 s7, s5, 0
	v_writelane_b32 v247, s6, 16
	v_mov_b32_e32 v1, 0
	s_brev_b32 s70, -2
	v_writelane_b32 v247, s7, 17
	s_add_u32 s6, s2, 0xf40000
	s_addc_u32 s7, s3, 0
	v_writelane_b32 v247, s6, 18
	s_brev_b32 s83, -4
	v_mov_b32_e32 v146, 0x260
	v_writelane_b32 v247, s7, 19
	s_add_u32 s6, s4, 0x98
	s_addc_u32 s7, s5, 0
	v_writelane_b32 v247, s6, 20
	v_mov_b32_e32 v136, 0x3a83126f
	v_mov_b32_e32 v147, 0x34f
	v_writelane_b32 v247, s7, 21
	s_add_u32 s6, s2, 0xd40000
	s_addc_u32 s7, s3, 0
	v_writelane_b32 v247, s6, 22
	v_mov_b32_e32 v148, 0xf149f2ca
	v_mov_b32_e32 v149, 0x447a0000
	v_writelane_b32 v247, s7, 23
	s_add_u32 s6, s4, 0x90
	s_addc_u32 s7, s5, 0
	v_writelane_b32 v247, s6, 24
	v_mov_b32_e32 v150, 0x7149f2ca
	s_nop 0
	v_writelane_b32 v247, s7, 25
	s_add_u32 s6, s2, 0xb40000
	s_addc_u32 s7, s3, 0
	v_writelane_b32 v247, s6, 26
	s_nop 1
	v_writelane_b32 v247, s7, 27
	s_add_u32 s6, s4, 0x88
	s_addc_u32 s7, s5, 0
	v_writelane_b32 v247, s6, 28
	s_add_u32 s4, s4, 0x80
	s_addc_u32 s5, s5, 0
	v_writelane_b32 v247, s7, 29
	v_writelane_b32 v247, s4, 30
	s_nop 1
	v_writelane_b32 v247, s5, 31
	s_add_u32 s4, s2, 0xa40000
	s_addc_u32 s5, s3, 0
	v_writelane_b32 v247, s4, 32
	s_nop 1
	v_writelane_b32 v247, s5, 33
	s_add_u32 s4, s2, 0x1e3d4100
	v_writelane_b32 v247, s4, 34
	s_addc_u32 s4, s3, 0
	v_writelane_b32 v247, s4, 35
	s_add_u32 s4, s2, 0x1e414100
	s_addc_u32 s5, s3, 0
	v_writelane_b32 v247, s4, 36
	s_nop 1
	v_writelane_b32 v247, s5, 37
	s_add_u32 s4, s2, 0x2bd4100
	v_writelane_b32 v247, s4, 38
	s_addc_u32 s4, s3, 0
	v_writelane_b32 v247, s4, 39
	s_add_u32 s4, s2, 0x163d4100
	v_writelane_b32 v247, s4, 40
	s_addc_u32 s4, s3, 0
	v_writelane_b32 v247, s4, 41
	s_add_u32 s4, s2, 0x1a3d4100
	v_writelane_b32 v247, s4, 42
	s_addc_u32 s4, s3, 0
	v_writelane_b32 v247, s4, 43
	v_writelane_b32 v247, s1, 44
	s_add_i32 s1, s1, 32
	s_add_i32 s4, s0, 32
	v_writelane_b32 v247, s4, 45
	s_add_i32 s1, s1, 0x12800
	v_writelane_b32 v247, s1, 46
	s_lshl_b32 s5, s89, 4
	s_lshr_b32 s1, s82, 8
	v_writelane_b32 v247, s89, 47
	s_and_b32 s45, s5, 48
	v_writelane_b32 v247, s5, 48
	s_add_u32 s94, s2, 0x23d4100
	s_mul_i32 s5, s1, 6
	s_addc_u32 s95, s3, 0
	v_writelane_b32 v247, s5, 49
	s_lshl_b32 s5, s1, 7
	s_add_u32 s6, s2, 0x2ad4100
	v_writelane_b32 v247, s6, 51
	s_addc_u32 s6, s3, 0
	v_writelane_b32 v247, s6, 52
	s_add_u32 s6, s2, 0x2b54100
	v_writelane_b32 v247, s6, 53
	s_addc_u32 s6, s3, 0
	v_writelane_b32 v247, s6, 54
	s_add_u32 s6, s2, 0xf3d4100
	s_addc_u32 s7, s3, 0
	s_add_u32 s86, s2, 0x113d4100
	v_writelane_b32 v247, s6, 55
	s_addc_u32 s87, s3, 0
	s_mul_i32 s4, s1, 0x8400
	v_writelane_b32 v247, s7, 56
	s_add_u32 s6, s2, 0x1fd0040
	s_addc_u32 s7, s3, 0
	v_writelane_b32 v247, s6, 57
	s_mulk_i32 s1, 0x1080
	s_mov_b32 s89, 0
	v_writelane_b32 v247, s7, 58
	s_add_u32 s6, s2, 0x143d4100
	v_writelane_b32 v247, s6, 59
	s_addc_u32 s6, s3, 0
	v_writelane_b32 v247, s6, 60
	s_add_u32 s6, s2, 0x14bd4100
	v_writelane_b32 v247, s6, 61
	s_addc_u32 s6, s3, 0
	v_writelane_b32 v247, s6, 62
	s_add_u32 s6, s2, 0x153d4100
	v_writelane_b32 v247, s6, 63
	s_addc_u32 s6, s3, 0
	v_writelane_b32 v246, s6, 0
	s_add_u32 s6, s2, 0x15bd4100
	v_writelane_b32 v246, s6, 1
	s_addc_u32 s6, s3, 0
	s_add_u32 s78, s2, 0x183d4100
	v_writelane_b32 v246, s6, 2
	s_addc_u32 s79, s3, 0
	s_addk_i32 s0, 0x2000
	v_writelane_b32 v246, s0, 3
	s_add_i32 s0, s4, 32
	s_add_i32 s0, s0, 0xd800
	v_writelane_b32 v246, s0, 4
	s_bfe_u32 s0, s82, 0x20006
	s_lshl_b32 s2, s0, 8
	v_writelane_b32 v246, s5, 5
	s_add_i32 s2, s2, s5
	s_mulk_i32 s0, 0x2100
	v_writelane_b32 v246, s2, 6
	s_add_i32 s0, s0, s1
	v_writelane_b32 v246, s0, 7
	s_add_i32 s2, 32, 0x1e010
	v_writelane_b32 v246, s2, 8
	s_add_i32 s2, 32, 0x1e020
	v_writelane_b32 v246, s2, 9
	s_add_i32 s2, 32, 0x1e030
	v_writelane_b32 v246, s2, 10
	s_add_i32 s2, 32, 0x1e040
	v_writelane_b32 v246, s2, 11
	s_add_i32 s2, 32, 0x1e050
	v_writelane_b32 v246, s2, 12
	s_add_i32 s2, 32, 0x1e060
	v_writelane_b32 v246, s2, 13
	s_add_i32 s2, 32, 0x1e070
	s_movk_i32 s0, 0x7f
	s_mov_b32 s1, 0xf149f2ca
	s_mov_b32 s82, 0xefa18f08
	v_writelane_b32 v246, s2, 14
	v_writelane_b32 v246, s45, 15
	v_cmp_eq_u32_e32 vcc, 0, v137
	s_and_saveexec_b64 s[2:3], vcc
	s_cbranch_execz .Lmy_q_init_done
	v_mov_b32_e32 v253, 1
	v_readlane_b32 s6, v247, 10
	v_readlane_b32 s7, v247, 11
	s_nop 4
	global_atomic_add v252, v1, v253, s[6:7] sc0
; DI void nsa_item(int wv0, PP p, int item, unsigned char* smem) {
;     ...
;   u16* NSAb = (u16*)(p->ws + OFF_NSA);
; #pragma unroll
;   for (int qt = 0; qt < 2; ++qt) {
;     float s = l[qt];
;     s += __shfl_xor(s, 16);
;     s += __shfl_xor(s, 32);
;     const float sc = NGb[ngoff + qt * 3 + 2] / s;
; #pragma unroll
;     for (int dt = 0; dt < 4; ++dt) {
;       const float4 a = *(const float4*)(ACCb + (aoff + qt * 64 + 16 * dt));
;       uint2 o;
;       o.x = pk2(a.x + O[qt][dt][0] * sc, a.y + O[qt][dt][1] * sc);
;       o.y = pk2(a.z + O[qt][dt][2] * sc, a.w + O[qt][dt][3] * sc);
;       *(uint2*)(NSAb + (aoff + qt * 64 + 16 * dt)) = o;
;     }
;   }
.Lmy_q_init_done:
	s_or_b64 exec, exec, s[2:3]
	s_branch .LBB0_726
.LBB0_723:
	v_add_u32_e32 v2, 2, v142
	v_mov_b32_e32 v3, v1
	v_lshl_add_u64 v[2:3], v[2:3], 2, s[94:95]
	global_load_dword v0, v[2:3], off
	v_add_u32_e32 v2, 5, v142
	v_mov_b32_e32 v3, v1
	v_lshl_add_u64 v[2:3], v[2:3], 2, s[94:95]
	global_load_dword v200, v[2:3], off
	s_nop 0
	ds_bpermute_b32 v6, v144, v29
	v_readlane_b32 s45, v246, 15
	s_waitcnt lgkmcnt(0)
	v_add_f32_e32 v6, v29, v6
	ds_bpermute_b32 v7, v145, v6
	s_waitcnt lgkmcnt(0)
	v_add_f32_e32 v8, v6, v7
	v_lshl_add_u64 v[6:7], v[138:139], 1, s[78:79]
	s_waitcnt vmcnt(0)
	v_div_scale_f32 v9, s[2:3], v8, v8, v0
	v_rcp_f32_e32 v10, v9
	v_div_scale_f32 v11, vcc, v0, v8, v0
	v_fma_f32 v12, -v9, v10, 1.0
	v_fmac_f32_e32 v10, v12, v10
	v_mul_f32_e32 v12, v11, v10
	v_fma_f32 v13, -v9, v12, v11
	v_fmac_f32_e32 v12, v13, v10
	v_fma_f32 v9, -v9, v12, v11
	v_div_fmas_f32 v9, v9, v10, v12
	v_div_fixup_f32 v8, v9, v8, v0
	v_pk_fma_f32 v[2:3], v[104:105], v[8:9], v[218:219] op_sel_hi:[1,0,1]
	v_pk_fma_f32 v[4:5], v[106:107], v[8:9], v[220:221] op_sel_hi:[1,0,1]
	v_cvt_pk_bf16_f32 v2, v2, v3
	v_cvt_pk_bf16_f32 v3, v4, v5
	global_store_dwordx2 v[6:7], v[2:3], off
	v_or_b32_e32 v0, 16, v138
	v_lshl_add_u64 v[6:7], v[0:1], 1, s[78:79]
	v_add_u32_e32 v0, 5, v142
	v_lshl_add_u64 v[10:11], v[0:1], 2, s[94:95]
	v_pk_fma_f32 v[2:3], v[112:113], v[8:9], v[222:223] op_sel_hi:[1,0,1]
	v_pk_fma_f32 v[4:5], v[114:115], v[8:9], v[224:225] op_sel_hi:[1,0,1]
	v_cvt_pk_bf16_f32 v2, v2, v3
	v_cvt_pk_bf16_f32 v3, v4, v5
	global_store_dwordx2 v[6:7], v[2:3], off
	v_or_b32_e32 v6, 32, v138
	v_mov_b32_e32 v7, v1
	v_lshl_add_u64 v[6:7], v[6:7], 1, s[78:79]
	v_pk_fma_f32 v[2:3], v[120:121], v[8:9], v[226:227] op_sel_hi:[1,0,1]
	v_pk_fma_f32 v[4:5], v[122:123], v[8:9], v[228:229] op_sel_hi:[1,0,1]
	v_cvt_pk_bf16_f32 v2, v2, v3
	v_cvt_pk_bf16_f32 v3, v4, v5
	global_store_dwordx2 v[6:7], v[2:3], off
	v_or_b32_e32 v6, 48, v138
	v_mov_b32_e32 v7, v1
	v_lshl_add_u64 v[6:7], v[6:7], 1, s[78:79]
	v_pk_fma_f32 v[2:3], v[128:129], v[8:9], v[230:231] op_sel_hi:[1,0,1]
	v_pk_fma_f32 v[4:5], v[130:131], v[8:9], v[232:233] op_sel_hi:[1,0,1]
	v_cvt_pk_bf16_f32 v2, v2, v3
	v_cvt_pk_bf16_f32 v3, v4, v5
	global_store_dwordx2 v[6:7], v[2:3], off
	ds_bpermute_b32 v6, v144, v26
	v_mov_b32_e32 v7, v1
	s_waitcnt lgkmcnt(0)
	v_add_f32_e32 v8, v26, v6
	ds_bpermute_b32 v9, v145, v8
	v_or_b32_e32 v6, 64, v138
	v_lshl_add_u64 v[6:7], v[6:7], 1, s[78:79]
	s_waitcnt lgkmcnt(0)
	v_add_f32_e32 v8, v8, v9
	v_div_scale_f32 v9, s[2:3], v8, v8, v200
	v_rcp_f32_e32 v10, v9
	v_div_scale_f32 v11, vcc, v200, v8, v200
	v_fma_f32 v12, -v9, v10, 1.0
	v_fmac_f32_e32 v10, v12, v10
	v_mul_f32_e32 v12, v11, v10
	v_fma_f32 v13, -v9, v12, v11
	v_fmac_f32_e32 v12, v13, v10
	v_fma_f32 v9, -v9, v12, v11
	v_div_fmas_f32 v9, v9, v10, v12
	v_div_fixup_f32 v0, v9, v8, v200
	v_pk_fma_f32 v[2:3], v[100:101], v[0:1], v[234:235] op_sel_hi:[1,0,1]
	v_pk_fma_f32 v[4:5], v[102:103], v[0:1], v[236:237] op_sel_hi:[1,0,1]
	v_cvt_pk_bf16_f32 v2, v2, v3
	v_cvt_pk_bf16_f32 v3, v4, v5
	global_store_dwordx2 v[6:7], v[2:3], off
	v_or_b32_e32 v6, 0x50, v138
	v_mov_b32_e32 v7, v1
	v_lshl_add_u64 v[6:7], v[6:7], 1, s[78:79]
	v_pk_fma_f32 v[2:3], v[108:109], v[0:1], v[238:239] op_sel_hi:[1,0,1]
	v_pk_fma_f32 v[4:5], v[110:111], v[0:1], v[240:241] op_sel_hi:[1,0,1]
	v_cvt_pk_bf16_f32 v2, v2, v3
	v_cvt_pk_bf16_f32 v3, v4, v5
	global_store_dwordx2 v[6:7], v[2:3], off
	v_or_b32_e32 v6, 0x60, v138
	v_mov_b32_e32 v7, v1
	v_lshl_add_u64 v[6:7], v[6:7], 1, s[78:79]
	v_pk_fma_f32 v[2:3], v[116:117], v[0:1], v[242:243] op_sel_hi:[1,0,1]
	v_pk_fma_f32 v[4:5], v[118:119], v[0:1], v[244:245] op_sel_hi:[1,0,1]
	v_cvt_pk_bf16_f32 v2, v2, v3
	v_cvt_pk_bf16_f32 v3, v4, v5
	global_store_dwordx2 v[6:7], v[2:3], off
	v_or_b32_e32 v6, 0x70, v138
	v_mov_b32_e32 v7, v1
	v_lshl_add_u64 v[6:7], v[6:7], 1, s[78:79]
	v_pk_fma_f32 v[2:3], v[124:125], v[0:1], v[248:249] op_sel_hi:[1,0,1]
	v_pk_fma_f32 v[4:5], v[126:127], v[0:1], v[250:251] op_sel_hi:[1,0,1]
	v_cvt_pk_bf16_f32 v2, v2, v3
	v_cvt_pk_bf16_f32 v3, v4, v5
	global_store_dwordx2 v[6:7], v[2:3], off
	s_barrier

; DI void phaseE(int wv0, PP p, unsigned char* smem, int cidx) {
;     ...
;   for (;;) {
;     __syncthreads();
;     if (my_tid(wv0) == 0) s_item = atomicAdd(ctr, 1);
;     __syncthreads();
;     const int item = s_item;
.LBB0_726:
	v_mov_b32_e32 v0, v137
	s_waitcnt vmcnt(0)
	s_barrier
	s_nop 0
	v_cmp_eq_u32_e32 vcc, 0, v0
	s_and_saveexec_b64 s[2:3], vcc
	s_cbranch_execz .LBB0_730
	ds_write_b32 v1, v252 offset:16
	v_mov_b32_e32 v253, 1
	v_readlane_b32 s6, v247, 10
	v_readlane_b32 s7, v247, 11
	s_nop 4
	global_atomic_add v252, v1, v253, s[6:7] sc0

; template <bool OUT>
; DI void s5_item(int wv0, PP p, int item, unsigned char* smem) {
;   const int tid = my_tid(wv0), lane = tid & 63, fr = lane & 15, fq = lane >> 4;
;   const int b = item >> 9, g = (item >> 4) & 31, c8 = item & 15, ch = c8 * 8 + wv0;
;   u16* sBb = (u16*)smem;
;   u16* sCm = sBb + 128 * 16;
;   float* sBU = (float*)(smem + 8192) + wv0 * (16 * 132);
;   u16* sH = (u16*)(smem + 8192 + 8 * 16 * 132 * 4) + wv0 * (16 * 136);
;   *(uint4*)(smem + tid * 16) = *(const uint4*)(p->ws + OFF_S5T + (size_t)g * 8192 + tid * 16);
;   const float2 lb = ((const float2*)(p->ws + OFF_S5L))[g * 64 + lane];
;   const float lbr = lb.x, lbi = lb.y;
;   float2* HL = (float2*)(p->ws + OFF_HLOC) + ((size_t)(b * 128 + ch) * 32 + g) * 64 + lane;
;   float hr = 0.f, hi = 0.f;
;   if (OUT) { const float2 h0 = *HL; hr = h0.x; hi = h0.y; }
;   const u16* U = (const u16*)(p->ws + OFF_U) + ((size_t)(b * S_ + ch * 64)) * 512 + g * 16;
;   u16* YS = (u16*)(p->ws + OFF_YS) + ((size_t)(b * S_ + ch * 64)) * 512 + g * 16;
;   const float dk = p->dsk[g * 16 + fr];
;   const bf16x8 zero8 = {0, 0, 0, 0, 0, 0, 0, 0};
;   bf16x8 uall[4];
;   u16 usk[4][4];
; #pragma unroll
;   for (int sub = 0; sub < 4; ++sub) {
;     uall[sub] = fq < 2 ? *(const bf16x8*)(U + (size_t)(sub * 16 + fr) * 512 + 8 * fq) : zero8;
.LBB0_758:
	s_and_b64 vcc, exec, s[2:3]
	s_cbranch_vccz .LBB0_822
	s_add_i32 s2, s16, 0xfffffc00
	s_lshr_b32 s4, s2, 9
	s_lshl_b32 s2, s2, 3
	s_bfe_u32 s6, s16, 0x50004
	s_and_b32 s2, s2, 0x78
	v_readlane_b32 s3, v247, 47
	v_mov_b32_e32 v6, v137
	s_add_i32 s5, s2, s3
	s_lshl_b32 s2, s6, 13
	v_readlane_b32 s3, v247, 34
	s_add_u32 s2, s3, s2
	v_readlane_b32 s3, v247, 35
	v_lshlrev_b32_e32 v8, 4, v6
	v_and_b32_e32 v82, 63, v6
	s_addc_u32 s3, s3, 0
	v_ashrrev_i32_e32 v9, 31, v8
	v_lshl_add_u64 v[2:3], s[2:3], 0, v[8:9]
	s_lshl_b32 s7, s6, 9
	v_lshlrev_b32_e32 v0, 3, v82
	v_readlane_b32 s2, v247, 36
	v_or_b32_e32 v4, s7, v0
	v_readlane_b32 s3, v247, 37
	v_readlane_b32 s8, v247, 38
	v_and_b32_e32 v70, 15, v6
	v_mov_b32_e32 v58, 0
	v_mov_b32_e32 v62, 0
	v_mov_b32_e32 v63, 0
	global_load_dwordx2 v[66:67], v4, s[2:3]
	s_lshl_b32 s2, s4, 7
	s_add_i32 s88, s5, s2
	s_lshl_b64 s[2:3], s[88:89], 14
	s_add_u32 s2, s8, s2
	v_readlane_b32 s8, v247, 39
	s_addc_u32 s3, s8, s3
	s_add_u32 s2, s2, s7
	s_addc_u32 s3, s3, 0
	global_load_dwordx4 v[200:203], v[2:3], off
	s_nop 0
	global_load_dwordx2 v[68:69], v0, s[2:3]
	s_lshl_b32 s2, s4, 13
	s_lshl_b32 s3, s5, 6
	s_add_i32 s88, s3, s2
	s_lshl_b64 s[2:3], s[88:89], 10
	v_readlane_b32 s4, v247, 40
	s_add_u32 s2, s4, s2
	v_readlane_b32 s4, v247, 5
	v_readlane_b32 s5, v247, 6
	s_load_dwordx2 s[4:5], s[4:5], 0x78
	v_readlane_b32 s7, v247, 41
	s_addc_u32 s3, s7, s3
	s_lshl_b32 s8, s6, 4
	v_or_b32_e32 v0, s8, v70
	v_lshlrev_b32_e32 v0, 2, v0
	s_waitcnt lgkmcnt(0)
	global_load_dword v72, v0, s[4:5]
	s_lshl_b32 s4, s6, 5
	v_add_u32_e32 v204, 32, v8
	s_add_u32 s4, s2, s4
	s_addc_u32 s5, s3, 0
	v_cmp_gt_u32_e64 s[2:3], 32, v82
	v_mov_b32_e32 v64, 0
	v_mov_b32_e32 v65, 0
	v_lshlrev_b32_e32 v4, 9, v70
	v_and_b32_e32 v0, 48, v6
	v_lshl_add_u64 v[2:3], s[4:5], 0, v[0:1]
	v_lshlrev_b32_e32 v4, 1, v4
	s_and_saveexec_b64 s[6:7], s[2:3]
	s_cbranch_execz .LBB0_761
	v_mov_b32_e32 v5, v1
	v_lshl_add_u64 v[8:9], v[2:3], 0, v[4:5]
	global_load_dwordx4 v[62:65], v[8:9], off

; DI f32x4 mfma16(bf16x8 a, bf16x8 b, f32x4 c) { return __builtin_amdgcn_mfma_f32_16x16x32_bf16(a, b, c, 0, 0, 0); }
; template <bool OUT>
; DI void s5_item(int wv0, PP p, int item, unsigned char* smem) {
;     ...
;     uall[sub] = fq < 2 ? *(const bf16x8*)(U + (size_t)(sub * 16 + fr) * 512 + 8 * fq) : zero8;
;     if (OUT) {
; #pragma unroll
;       for (int j = 0; j < 4; ++j) usk[sub][j] = U[(size_t)(sub * 16 + 4 * fq + j) * 512 + fr];
;     }
;   }
;   __syncthreads();
;   bf16x8 bb[8], cf[4];
; #pragma unroll
;   for (int nt = 0; nt < 8; ++nt) bb[nt] = fq < 2 ? *(const bf16x8*)(sBb + (16 * nt + fr) * 16 + 8 * fq) : zero8;
;   if (OUT) {
; #pragma unroll
;     for (int ks = 0; ks < 4; ++ks) cf[ks] = *(const bf16x8*)(sCm + fr * 128 + 32 * ks + 8 * fq);
;   }
; #pragma unroll
;   for (int sub = 0; sub < 4; ++sub) {
;     const bf16x8 ua = uall[sub];
; #pragma unroll
;     for (int nt = 0; nt < 8; ++nt) {
;       const f32x4 a = mfma16(ua, bb[nt], f32x4{0.f, 0.f, 0.f, 0.f});
; #pragma unroll
;       for (int j = 0; j < 4; ++j) sBU[(4 * fq + j) * 132 + 16 * nt + fr] = a[j];
;     }
;     __syncthreads();
.LBB0_767:
	s_or_b64 exec, exec, s[6:7]
	v_or_b32_e32 v2, 0x6000, v6
	v_lshlrev_b32_e32 v79, 1, v2
	v_or_b32_e32 v2, 0x6200, v6
	v_lshlrev_b32_e32 v77, 1, v2
	v_or_b32_e32 v2, 0x6400, v6
	v_lshlrev_b32_e32 v75, 1, v2
	v_or_b32_e32 v2, 0x6600, v6
	v_lshlrev_b32_e32 v73, 1, v2
	global_load_ushort v80, v79, s[4:5]
	global_load_ushort v78, v77, s[4:5]
	global_load_ushort v76, v75, s[4:5]
	global_load_ushort v74, v73, s[4:5]
	v_lshl_add_u32 v2, v70, 5, 32
	v_mov_b32_e32 v22, 0
	v_add_u32_e32 v3, v2, v0
	v_mov_b32_e32 v26, 0
	v_mov_b32_e32 v27, 0
	v_mov_b32_e32 v28, 0
	v_mov_b32_e32 v29, 0
	s_waitcnt vmcnt(22)
	ds_write_b128 v204, v[200:203]
	s_waitcnt lgkmcnt(0)
	s_barrier
	s_and_saveexec_b64 s[4:5], s[2:3]
	ds_read_b128 v[26:29], v3
	s_or_b64 exec, exec, s[4:5]
	v_mov_b32_e32 v23, 0
	v_mov_b32_e32 v24, 0
	v_mov_b32_e32 v25, 0
	s_and_saveexec_b64 s[4:5], s[2:3]
	ds_read_b128 v[22:25], v3 offset:512
	s_or_b64 exec, exec, s[4:5]
	v_mov_b32_e32 v30, 0
	v_mov_b32_e32 v34, 0
	v_mov_b32_e32 v35, 0
	v_mov_b32_e32 v36, 0
	v_mov_b32_e32 v37, 0
	s_and_saveexec_b64 s[4:5], s[2:3]
	ds_read_b128 v[34:37], v3 offset:1024
	s_or_b64 exec, exec, s[4:5]
	v_mov_b32_e32 v31, 0
	v_mov_b32_e32 v32, 0
	v_mov_b32_e32 v33, 0
	s_and_saveexec_b64 s[4:5], s[2:3]
	ds_read_b128 v[30:33], v3 offset:1536
	s_or_b64 exec, exec, s[4:5]
	v_mov_b32_e32 v38, 0
	v_mov_b32_e32 v42, 0
	v_mov_b32_e32 v43, 0
	v_mov_b32_e32 v44, 0
	v_mov_b32_e32 v45, 0
	s_and_saveexec_b64 s[4:5], s[2:3]
	ds_read_b128 v[42:45], v3 offset:2048
	s_or_b64 exec, exec, s[4:5]
	v_mov_b32_e32 v39, 0
	v_mov_b32_e32 v40, 0
	v_mov_b32_e32 v41, 0
	s_and_saveexec_b64 s[4:5], s[2:3]
	ds_read_b128 v[38:41], v3 offset:2560
	s_or_b64 exec, exec, s[4:5]
	v_mov_b32_e32 v46, 0
	v_mov_b32_e32 v50, 0
	v_mov_b32_e32 v51, 0
	v_mov_b32_e32 v52, 0
	v_mov_b32_e32 v53, 0
	s_and_saveexec_b64 s[4:5], s[2:3]
	ds_read_b128 v[50:53], v3 offset:3072
	s_or_b64 exec, exec, s[4:5]
	v_mov_b32_e32 v47, 0
	v_mov_b32_e32 v48, 0
	v_mov_b32_e32 v49, 0
	s_and_saveexec_b64 s[4:5], s[2:3]
	ds_read_b128 v[46:49], v3 offset:3584
	s_or_b64 exec, exec, s[4:5]
	v_readlane_b32 s4, v247, 45
	s_waitcnt vmcnt(16) lgkmcnt(0)
	v_mfma_f32_16x16x32_bf16 v[112:115], v[62:65], v[26:29], 0
	v_mul_u32_u24_e32 v3, 0xe0, v70
	v_lshl_add_u32 v105, v70, 2, s4
	s_movk_i32 s4, 0x840
	v_mul_u32_u24_e32 v110, 0x110, v70
	v_mad_u32_u24 v70, v71, s4, v105
	s_movk_i32 s4, 0x210
	v_add3_u32 v2, v2, v3, v0
	v_mul_u32_u24_e32 v106, 0x840, v71
	v_mad_u32_u24 v71, v81, s4, v105
	ds_read_b128 v[14:17], v2 offset:4096
	ds_read_b128 v[10:13], v2 offset:4160
	ds_read_b128 v[6:9], v2 offset:4224
	ds_read_b128 v[2:5], v2 offset:4288
	ds_write_b32 v70, v112 offset:8192
	ds_write_b32 v71, v113 offset:8192
	ds_write_b32 v71, v114 offset:8720
	ds_write_b32 v71, v115 offset:9248
	v_mfma_f32_16x16x32_bf16 v[112:115], v[62:65], v[22:25], 0
	s_nop 7
	ds_write_b32 v70, v112 offset:8256
	ds_write_b32 v71, v113 offset:8256
	ds_write_b32 v71, v114 offset:8784
	ds_write_b32 v71, v115 offset:9312
	v_mfma_f32_16x16x32_bf16 v[112:115], v[62:65], v[34:37], 0
	s_nop 7
	ds_write_b32 v70, v112 offset:8320
	ds_write_b32 v71, v113 offset:8320
	ds_write_b32 v71, v114 offset:8848
	ds_write_b32 v71, v115 offset:9376
	v_mfma_f32_16x16x32_bf16 v[112:115], v[62:65], v[30:33], 0
	s_nop 7
	ds_write_b32 v70, v112 offset:8384
	ds_write_b32 v71, v113 offset:8384
	ds_write_b32 v71, v114 offset:8912
	ds_write_b32 v71, v115 offset:9440
	v_mfma_f32_16x16x32_bf16 v[112:115], v[62:65], v[42:45], 0
	s_nop 7
	ds_write_b32 v70, v112 offset:8448
	ds_write_b32 v71, v113 offset:8448
	ds_write_b32 v71, v114 offset:8976
	ds_write_b32 v71, v115 offset:9504
	v_mfma_f32_16x16x32_bf16 v[112:115], v[62:65], v[38:41], 0
	s_nop 7
	ds_write_b32 v70, v112 offset:8512
	ds_write_b32 v71, v113 offset:8512
	ds_write_b32 v71, v114 offset:9040
	ds_write_b32 v71, v115 offset:9568
	v_mfma_f32_16x16x32_bf16 v[112:115], v[62:65], v[50:53], 0
	v_readlane_b32 s4, v247, 44
	v_mul_u32_u24_e32 v107, 0x210, v81
	s_lshl_b64 s[2:3], s[88:89], 9
	v_mfma_f32_16x16x32_bf16 v[62:65], v[62:65], v[46:49], 0
	v_lshl_add_u32 v81, v82, 1, s4
	v_readlane_b32 s4, v246, 3
	s_nop 1
	ds_write_b32 v70, v112 offset:8576
	ds_write_b32 v71, v113 offset:8576
	ds_write_b32 v71, v114 offset:9104
	ds_write_b32 v71, v115 offset:9632
	v_lshl_add_u32 v82, v82, 2, s4
	ds_write_b32 v70, v62 offset:8640
	ds_write_b32 v71, v63 offset:8640
	ds_write_b32 v71, v64 offset:9168
	ds_write_b32 v71, v65 offset:9696
	v_pk_mov_b32 v[70:71], v[66:67], v[66:67] op_sel:[1,0]
	s_mov_b32 s4, 16
	v_mov_b32_e32 v62, v82
	v_mov_b32_e32 v63, v81
	s_waitcnt lgkmcnt(0)
	s_barrier

; DI void nsa_item(int wv0, PP p, int item, unsigned char* smem) {
;     ...
; #pragma unroll
;     for (int qt = 0; qt < 2; ++qt) {
;       const float gt = NGb[ngoff + qt * 3 + 0];
; #pragma unroll
;       for (int dt = 0; dt < 4; ++dt) {
;         float4 o = make_float4(O[qt][dt][0] * gt, O[qt][dt][1] * gt, O[qt][dt][2] * gt, O[qt][dt][3] * gt);
;         *(float4*)(ACCb + (aoff + qt * 64 + 16 * dt)) = o;
;       }
;     }
;   }
;   __syncthreads();
;   u64 mlo = 0, mhi = 0, wlo = 0, whi = 0;
;   if (i < 16) {
;     mlo = (1ull << (i + 1)) - 1ull;
;     wlo = mlo;
;   } else {
;     const bool v0 = lane <= i, v1 = (lane + 64) <= i;
;     const bool f0 = (lane == 0) || (lane == i) || (lane == i - 1);
;     const bool f1 = (lane + 64 == i) || (lane + 64 == i - 1);
;     const u64 ltm = (1ull << lane) - 1ull;
.LBB0_813:
	s_mul_i32 s2, s40, 12
	v_readlane_b32 s3, v247, 49
	s_add_i32 s2, s2, s3
	v_mov_b32_e32 v2, s2
	v_mad_u64_u32 v[142:143], s[2:3], v74, 24, v[2:3]
	v_mov_b32_e32 v143, v1
	v_lshl_add_u64 v[2:3], v[142:143], 2, s[94:95]
	global_load_dword v16, v[2:3], off
	v_readlane_b32 s2, v247, 5
	v_readlane_b32 s3, v247, 6
	s_load_dwordx2 s[2:3], s[2:3], 0xc0
	v_or_b32_e32 v138, v72, v153
	v_mov_b32_e32 v139, v1
	v_mov_b32_e32 v3, v1
	v_add_u32_e32 v2, 3, v142
	s_waitcnt lgkmcnt(0)
	v_lshl_add_u64 v[140:141], v[138:139], 2, s[2:3]
	s_waitcnt vmcnt(1)
	v_lshl_add_u64 v[34:35], v[2:3], 2, s[94:95]
	global_load_dword v200, v[34:35], off
	s_mov_b64 s[2:3], -1
	s_cmpk_lt_i32 s88, 0x70
	v_cmp_eq_u32_e32 vcc, 0, v71
	s_waitcnt vmcnt(0)
	v_pk_mul_f32 v[2:3], v[54:55], v[16:17] op_sel_hi:[1,0]
	v_pk_mul_f32 v[4:5], v[56:57], v[16:17] op_sel_hi:[1,0]
	v_pk_mul_f32 v[6:7], v[50:51], v[16:17] op_sel_hi:[1,0]
	v_pk_mul_f32 v[8:9], v[52:53], v[16:17] op_sel_hi:[1,0]
	v_pk_mul_f32 v[10:11], v[46:47], v[16:17] op_sel_hi:[1,0]
	v_pk_mul_f32 v[12:13], v[48:49], v[16:17] op_sel_hi:[1,0]
	v_pk_mul_f32 v[14:15], v[42:43], v[16:17] op_sel_hi:[1,0]
	v_pk_mul_f32 v[16:17], v[44:45], v[16:17] op_sel_hi:[1,0]
	v_mov_b64_e32 v[218:219], v[2:3]
	v_mov_b64_e32 v[220:221], v[4:5]
	v_mov_b64_e32 v[222:223], v[6:7]
	v_mov_b64_e32 v[224:225], v[8:9]
	v_mov_b64_e32 v[226:227], v[10:11]
	v_mov_b64_e32 v[228:229], v[12:13]
	v_mov_b64_e32 v[230:231], v[14:15]
	v_mov_b64_e32 v[232:233], v[16:17]
	v_pk_mul_f32 v[2:3], v[30:31], v[200:201] op_sel_hi:[1,0]
	v_pk_mul_f32 v[4:5], v[32:33], v[200:201] op_sel_hi:[1,0]
	v_pk_mul_f32 v[6:7], v[26:27], v[200:201] op_sel_hi:[1,0]
	v_pk_mul_f32 v[8:9], v[28:29], v[200:201] op_sel_hi:[1,0]
	v_pk_mul_f32 v[10:11], v[22:23], v[200:201] op_sel_hi:[1,0]
	v_pk_mul_f32 v[12:13], v[24:25], v[200:201] op_sel_hi:[1,0]
	v_pk_mul_f32 v[14:15], v[18:19], v[200:201] op_sel_hi:[1,0]
	v_pk_mul_f32 v[16:17], v[20:21], v[200:201] op_sel_hi:[1,0]
	v_mov_b64_e32 v[234:235], v[2:3]
	v_mov_b64_e32 v[236:237], v[4:5]
	v_mov_b64_e32 v[238:239], v[6:7]
	v_mov_b64_e32 v[240:241], v[8:9]
	v_mov_b64_e32 v[242:243], v[10:11]
	v_mov_b64_e32 v[244:245], v[12:13]
	v_mov_b64_e32 v[248:249], v[14:15]
	v_mov_b64_e32 v[250:251], v[16:17]
	s_barrier
	s_cbranch_scc0 .LBB0_820
	v_cmp_eq_u32_e64 s[10:11], s33, v71
	s_sub_i32 s14, 0x7e, s88
	s_or_b64 s[12:13], vcc, s[10:11]
	v_cmp_eq_u32_e64 s[10:11], s14, v71
	v_or_b32_e32 v2, 64, v71
	s_or_b64 s[10:11], s[12:13], s[10:11]
	v_cndmask_b32_e64 v4, 0, v149, s[10:11]
	v_cmp_eq_u32_e64 s[10:11], s33, v2
	v_cmp_eq_u32_e64 s[12:13], s14, v2
	s_or_b64 s[10:11], s[10:11], s[12:13]
	v_cmp_lt_i32_e64 s[6:7], s33, v2
	v_cmp_ge_i32_e64 s[8:9], s33, v2
	v_cndmask_b32_e64 v5, 0, v149, s[10:11]
	v_lshlrev_b64 v[2:3], v71, -1
	v_readlane_b32 s10, v246, 7
	v_cmp_lt_i32_e64 s[2:3], s33, v71
	v_cmp_ge_i32_e64 s[4:5], s33, v71
	v_not_b32_e32 v3, v3
	v_not_b32_e32 v2, v2
	v_lshl_add_u32 v6, v71, 2, s10
	s_mov_b64 s[20:21], 0
	s_mov_b32 s24, 8
	v_readlane_b32 s25, v246, 6
	s_mov_b64 s[22:23], 0
	s_branch .LBB0_816

; #define ISSUE_TILE(RK, RV, T, LDV)                                                   \
;   {                                                                                  \
;     pk0 = BLOAD(RK, koff, (T)*8192);                                                 \
;     pv0 = BLOAD(RV, ((LDV) == 512) ? voffc : voffs, (T)*128);                        \
;   }
; DI void nsa_item(int wv0, PP p, int item, unsigned char* smem) {
;     ...
;       int j2 = j1 >= 0 ? next_bit(blo, bhi, j1 + 1) : -1;
;       if (j2 >= 0) ISSUE_TILE(rK, rV, j2, S_)
;       f32x4 sc_[2][4], sn_[2][4];
;       {
;         const bool selc = bit128(mlo, mhi, jc);
;         flash_s3(sK, qf, (selc || jc == i) ? m[0] : -1e30f, (selc || jc == i) ? m[1] : -1e30f, sc_, lane);
;       }
;       int bc = 0;
;     ...
;             auto ok = [&](int kt, int ii) { return sel && (16 * kt + 4 * lg + ii) <= qloc; };
.LBB0_875:
	s_cmp_lt_i32 s85, 64
	s_cselect_b64 vcc, -1, 0
	s_sub_i32 s2, s85, 64
	v_lshrrev_b64 v[2:3], s85, v[20:21]
	v_lshrrev_b64 v[30:31], s2, v[22:23]
	v_cndmask_b32_e32 v0, v30, v2, vcc
	v_and_b32_e32 v0, 1, v0
	v_mul_u32_u24_e32 v28, 0x48, v155
	v_cmp_eq_u32_e32 vcc, 1, v0
	v_lshl_add_u32 v0, v28, 1, v158
	ds_read_b128 v[30:33], v0
	ds_read_b128 v[34:37], v0 offset:64
	s_cmp_eq_u32 s85, s33
	s_cselect_b64 s[2:3], -1, 0
	s_or_b64 s[2:3], vcc, s[2:3]
	v_cndmask_b32_e64 v38, v148, -v29, s[2:3]
	v_mov_b32_e32 v39, v38
	v_mov_b32_e32 v40, v38
	v_mov_b32_e32 v41, v38
	ds_read_b128 v[46:49], v0 offset:2304
	ds_read_b128 v[54:57], v0 offset:4608
	s_waitcnt lgkmcnt(3)
	v_mfma_f32_16x16x32_bf16 v[42:45], v[30:33], v[4:7], v[38:41]
	v_cndmask_b32_e64 v70, v148, -v161, s[2:3]
	v_mov_b32_e32 v71, v70
	v_mov_b32_e32 v72, v70
	s_waitcnt lgkmcnt(2)
	v_mfma_f32_16x16x32_bf16 v[98:101], v[34:37], v[8:11], v[42:45]
	v_mov_b32_e32 v73, v70
	v_mul_u32_u24_e32 v164, 0x48, v157
	s_cmp_lt_i32 s85, 0
	ds_read_b128 v[42:45], v0 offset:2368
	s_waitcnt lgkmcnt(2)
	v_mfma_f32_16x16x32_bf16 v[50:53], v[46:49], v[4:7], v[38:41]
	s_waitcnt lgkmcnt(0)
	v_mfma_f32_16x16x32_bf16 v[102:105], v[42:45], v[8:11], v[50:53]
	s_nop 5
	ds_read_b128 v[50:53], v0 offset:4672
	v_lshl_add_u32 v0, v164, 1, v158
	ds_read_b128 v[66:69], v0
	v_mfma_f32_16x16x32_bf16 v[30:33], v[30:33], v[12:15], v[70:73]
	v_mfma_f32_16x16x32_bf16 v[58:61], v[54:57], v[4:7], v[38:41]
	v_mfma_f32_16x16x32_bf16 v[126:129], v[34:37], v[16:19], v[30:33]
	v_mfma_f32_16x16x32_bf16 v[30:33], v[46:49], v[12:15], v[70:73]
	s_waitcnt lgkmcnt(1)
	v_mfma_f32_16x16x32_bf16 v[118:121], v[50:53], v[8:11], v[58:61]
	s_nop 3
	ds_read_b128 v[58:61], v0 offset:64
	v_mfma_f32_16x16x32_bf16 v[114:117], v[42:45], v[16:19], v[30:33]
	v_mfma_f32_16x16x32_bf16 v[30:33], v[54:57], v[12:15], v[70:73]
	s_waitcnt lgkmcnt(1)
	v_mfma_f32_16x16x32_bf16 v[38:41], v[66:69], v[4:7], v[38:41]
	v_mfma_f32_16x16x32_bf16 v[110:113], v[50:53], v[16:19], v[30:33]
	v_mfma_f32_16x16x32_bf16 v[30:33], v[66:69], v[12:15], v[70:73]
	s_waitcnt lgkmcnt(0)
	v_mfma_f32_16x16x32_bf16 v[122:125], v[58:61], v[8:11], v[38:41]
	v_mfma_f32_16x16x32_bf16 v[106:109], v[58:61], v[16:19], v[30:33]
	s_cbranch_scc1 .LBB0_898
	v_or_b32_e32 v0, 2, v153
	v_cmp_gt_u32_e64 s[6:7], v0, v160
	v_or_b32_e32 v0, 3, v153
	v_cmp_gt_u32_e64 s[8:9], v0, v160
	v_or_b32_e32 v0, 16, v153
	v_cmp_gt_u32_e64 s[10:11], v0, v160
	v_or_b32_e32 v0, 17, v153
	v_cmp_gt_u32_e64 s[12:13], v0, v160
	v_or_b32_e32 v0, 18, v153
	v_cmp_gt_u32_e64 s[14:15], v0, v160
	v_or_b32_e32 v0, 19, v153
	v_cmp_gt_u32_e64 s[16:17], v0, v160
	v_or_b32_e32 v0, 32, v153
	v_cmp_gt_u32_e64 s[18:19], v0, v160
	v_or_b32_e32 v0, 33, v153
	v_cmp_gt_u32_e64 s[20:21], v0, v160
	v_or_b32_e32 v0, 34, v153
	v_cmp_gt_u32_e64 s[22:23], v0, v160
	v_or_b32_e32 v0, 35, v153
	v_cmp_gt_u32_e64 s[24:25], v0, v160
	v_or_b32_e32 v0, 48, v153
	v_cmp_gt_u32_e64 s[26:27], v0, v160
	v_or_b32_e32 v0, 49, v153
	v_cmp_gt_u32_e64 s[28:29], v0, v160
	v_or_b32_e32 v0, 50, v153
	v_cmp_gt_u32_e64 s[30:31], v0, v160
	v_or_b32_e32 v0, 51, v153
	v_mov_b32_e32 v2, v1
	v_mov_b32_e32 v3, v1
	v_cmp_gt_u32_e64 s[34:35], v0, v160
	v_mov_b32_e32 v0, v1
	v_mov_b64_e32 v[32:33], v[2:3]
	v_mov_b64_e32 v[36:37], v[2:3]
	v_mov_b64_e32 v[40:41], v[2:3]
	v_mov_b64_e32 v[44:45], v[2:3]
	v_mov_b64_e32 v[48:49], v[2:3]
	v_mov_b64_e32 v[52:53], v[2:3]
	v_mov_b64_e32 v[56:57], v[2:3]
	v_mov_b64_e32 v[60:61], v[2:3]
	v_cmp_gt_u32_e64 s[2:3], v153, v160
	v_cmp_lt_u32_e64 s[4:5], v153, v160
	s_mov_b32 s45, 0
	v_mov_b32_e32 v162, 0
	v_mov_b64_e32 v[30:31], v[0:1]
	v_mov_b64_e32 v[34:35], v[0:1]
	v_mov_b64_e32 v[38:39], v[0:1]
	v_mov_b64_e32 v[42:43], v[0:1]
	v_mov_b64_e32 v[46:47], v[0:1]
	v_mov_b64_e32 v[50:51], v[0:1]
	v_mov_b64_e32 v[54:55], v[0:1]
	v_mov_b64_e32 v[58:59], v[0:1]
	v_mov_b32_e32 v163, 0
	s_mov_b32 s32, 0
	s_branch .LBB0_879

; DI void nsa_item(int wv0, PP p, int item, unsigned char* smem) {
;     ...
;       while (jc >= 0) {
;         const int bn = bc == 2 ? 0 : bc + 1, bn2 = bn == 2 ? 0 : bn + 1;
;         const bool needn = j1 >= 0 && bit128(wlo, whi, j1);
;         if (needn) {
;           const bool seln = bit128(mlo, mhi, j1);
;           const bool on = seln || j1 == i;
;           flash_s3(sK + bn * 9216, qf, on ? m[0] : -1e30f, on ? m[1] : -1e30f, sn_, lane);
;         }
;         if (bit128(wlo, whi, jc)) {
;           if (jc == i) {
;             const bool sel = bit128(mlo, mhi, jc);
;             auto ok = [&](int kt, int ii) { return sel && (16 * kt + 4 * lg + ii) <= qloc; };
;             flash_pv3<true>(sV + bc * 9216, sc_, O, l, ok, lane);
;           } else {
;             flash_pv3<false>(sV + bc * 9216, sc_, O, l, nomask, lane);
;           }
;         }
.LBB0_878:
	s_mov_b32 s85, s42
	s_mov_b32 s42, s43
	s_mov_b32 s43, s40
	s_mov_b32 s45, s44
.LBB0_879:
	s_add_i32 s36, s45, 1
	s_cmp_lg_u32 s45, 2
	s_cselect_b32 s44, s36, 0
	s_cmp_lt_i32 s42, 0
	s_cselect_b64 s[38:39], -1, 0
	s_and_b64 vcc, exec, s[38:39]
	s_cbranch_vccnz .Lmy_selC_old882
	v_sub_co_u32_e64 v2, s[36:37], s42, 64
	v_lshrrev_b64 v[166:167], s42, v[130:131]
	v_lshrrev_b64 v[168:169], v2, v[134:135]
	v_cndmask_b32_e64 v0, v168, v166, s[36:37]
	v_and_b32_e32 v0, 1, v0
	v_cmp_eq_u64_e32 vcc, 0, v[0:1]
	s_cbranch_vccnz .Lmy_selC_old882
	s_cmp_eq_u32 s85, s33
	s_cbranch_scc1 .Lmy_selC_old
	v_sub_co_u32_e64 v196, s[40:41], s85, 64
	v_lshrrev_b64 v[186:187], s85, v[130:131]
	v_lshrrev_b64 v[188:189], v196, v[134:135]
	v_cndmask_b32_e64 v0, v188, v186, s[40:41]
	v_and_b32_e32 v0, 1, v0
	v_cmp_eq_u64_e32 vcc, 0, v[0:1]
	s_cbranch_vccz .Lmy_selC_disp
.Lmy_selC_old:
	s_cmp_eq_u32 s32, 0
	s_cbranch_scc1 .Lmy_selC_old2
	v_mov_b64_e32 v[108:109], v[96:97]
	v_mov_b64_e32 v[112:113], v[92:93]
	v_mov_b64_e32 v[116:117], v[88:89]
	v_mov_b64_e32 v[128:129], v[84:85]
	v_mov_b64_e32 v[124:125], v[80:81]
	v_mov_b64_e32 v[120:121], v[76:77]
	v_mov_b64_e32 v[104:105], v[72:73]
	v_mov_b64_e32 v[100:101], v[68:69]
	v_mov_b64_e32 v[106:107], v[94:95]
	v_mov_b64_e32 v[110:111], v[90:91]
	v_mov_b64_e32 v[114:115], v[86:87]
	v_mov_b64_e32 v[126:127], v[82:83]
	v_mov_b64_e32 v[122:123], v[78:79]
	v_mov_b64_e32 v[118:119], v[74:75]
	v_mov_b64_e32 v[102:103], v[70:71]
	v_mov_b64_e32 v[98:99], v[66:67]
.Lmy_selC_old2:
	v_lshrrev_b64 v[66:67], s42, v[20:21]
	v_lshrrev_b64 v[2:3], v2, v[22:23]
	v_cndmask_b32_e64 v0, v2, v66, s[36:37]
	v_and_b32_e32 v0, 1, v0
	s_mul_i32 s36, s44, 0x4800
	v_cmp_eq_u32_e32 vcc, 1, v0
	v_add_u32_e32 v0, s36, v158
	v_lshl_add_u32 v2, v28, 1, v0
	ds_read_b128 v[82:85], v2
	ds_read_b128 v[86:89], v2 offset:64
	s_cmp_eq_u32 s42, s33
	ds_read_b128 v[90:93], v2 offset:2304
	ds_read_b128 v[94:97], v2 offset:2368
	s_cselect_b64 s[36:37], -1, 0
	s_or_b64 s[36:37], vcc, s[36:37]
	v_cndmask_b32_e64 v78, v148, -v29, s[36:37]
	v_lshl_add_u32 v0, v164, 1, v0
	v_cndmask_b32_e64 v182, v148, -v161, s[36:37]
	v_mov_b32_e32 v79, v78
	v_mov_b32_e32 v80, v78
	v_mov_b32_e32 v81, v78
	ds_read_b128 v[166:169], v2 offset:4608
	ds_read_b128 v[170:173], v2 offset:4672
	ds_read_b128 v[174:177], v0
	ds_read_b128 v[178:181], v0 offset:64
	v_mov_b32_e32 v183, v182
	v_mov_b32_e32 v184, v182
	v_mov_b32_e32 v185, v182
	s_waitcnt lgkmcnt(7)
	v_mfma_f32_16x16x32_bf16 v[66:69], v[82:85], v[4:7], v[78:81]
	v_mfma_f32_16x16x32_bf16 v[82:85], v[82:85], v[12:15], v[182:185]
	s_waitcnt lgkmcnt(6)
	v_mfma_f32_16x16x32_bf16 v[66:69], v[86:89], v[8:11], v[66:69]
	s_waitcnt lgkmcnt(5)
	v_mfma_f32_16x16x32_bf16 v[70:73], v[90:93], v[4:7], v[78:81]
	v_mfma_f32_16x16x32_bf16 v[82:85], v[86:89], v[16:19], v[82:85]
	v_mfma_f32_16x16x32_bf16 v[86:89], v[90:93], v[12:15], v[182:185]
	s_waitcnt lgkmcnt(4)
	v_mfma_f32_16x16x32_bf16 v[70:73], v[94:97], v[8:11], v[70:73]
	s_waitcnt lgkmcnt(3)
	v_mfma_f32_16x16x32_bf16 v[74:77], v[166:169], v[4:7], v[78:81]
	s_waitcnt lgkmcnt(1)
	v_mfma_f32_16x16x32_bf16 v[78:81], v[174:177], v[4:7], v[78:81]
	v_mfma_f32_16x16x32_bf16 v[86:89], v[94:97], v[16:19], v[86:89]
	v_mfma_f32_16x16x32_bf16 v[90:93], v[166:169], v[12:15], v[182:185]
	v_mfma_f32_16x16x32_bf16 v[94:97], v[174:177], v[12:15], v[182:185]
	v_mfma_f32_16x16x32_bf16 v[74:77], v[170:173], v[8:11], v[74:77]
	s_waitcnt lgkmcnt(0)
	v_mfma_f32_16x16x32_bf16 v[78:81], v[178:181], v[8:11], v[78:81]
	v_mfma_f32_16x16x32_bf16 v[90:93], v[170:173], v[16:19], v[90:93]
	v_mfma_f32_16x16x32_bf16 v[94:97], v[178:181], v[16:19], v[94:97]
.LBB0_882:
	s_mov_b32 s32, 1
	v_sub_co_u32_e64 v196, s[36:37], s85, 64
	v_lshrrev_b64 v[2:3], s85, v[130:131]
	v_lshrrev_b64 v[166:167], v196, v[134:135]
	v_cndmask_b32_e64 v0, v166, v2, s[36:37]
	v_and_b32_e32 v0, 1, v0
	v_cmp_eq_u64_e32 vcc, 0, v[0:1]
	s_cbranch_vccnz .LBB0_888
	v_exp_f32_e32 v197, v98
	v_exp_f32_e32 v195, v99
	v_exp_f32_e32 v194, v100
	v_exp_f32_e32 v193, v101
	v_exp_f32_e32 v192, v102
	v_exp_f32_e32 v191, v103
	v_exp_f32_e32 v190, v104
	v_exp_f32_e32 v189, v105
	v_exp_f32_e32 v188, v118
	v_exp_f32_e32 v187, v119
	v_exp_f32_e32 v186, v120
	v_exp_f32_e32 v185, v121
	v_exp_f32_e32 v184, v122
	v_exp_f32_e32 v183, v123
	v_exp_f32_e32 v182, v124
	v_exp_f32_e32 v181, v125
	v_exp_f32_e32 v179, v126
	v_exp_f32_e32 v180, v127
	v_exp_f32_e32 v165, v128
	v_exp_f32_e32 v166, v129
	v_exp_f32_e32 v167, v114
	v_exp_f32_e32 v168, v115
	v_exp_f32_e32 v169, v116
	v_exp_f32_e32 v170, v117
	v_exp_f32_e32 v171, v110
	v_exp_f32_e32 v172, v111
	v_exp_f32_e32 v173, v112
	v_exp_f32_e32 v174, v113
	v_exp_f32_e32 v175, v106
	v_exp_f32_e32 v176, v107
	v_exp_f32_e32 v177, v108
	v_exp_f32_e32 v178, v109
	s_cmp_lg_u32 s85, s33
	s_mulk_i32 s45, 0x4800
	v_lshlrev_b32_e32 v160, 1, v28
	v_lshlrev_b32_e32 v3, 1, v164
	s_cbranch_scc1 .Lmy_sel_pv
	s_nop 3
	v_lshrrev_b64 v[98:99], s85, v[20:21]
	v_lshrrev_b64 v[100:101], v196, v[22:23]
	v_cndmask_b32_e64 v0, v100, v98, s[36:37]
	v_and_b32_e32 v0, 1, v0
	v_cmp_eq_u64_e32 vcc, 0, v[0:1]
	s_or_b64 s[40:41], vcc, s[2:3]
	s_or_b64 s[46:47], vcc, s[6:7]
	s_or_b64 s[48:49], vcc, s[8:9]
	s_or_b64 s[50:51], vcc, s[10:11]
	s_or_b64 s[52:53], vcc, s[12:13]
	s_or_b64 s[54:55], vcc, s[14:15]
	s_or_b64 s[56:57], vcc, s[16:17]
	s_or_b64 s[58:59], vcc, s[18:19]
	s_or_b64 s[60:61], vcc, s[20:21]
	s_or_b64 s[62:63], vcc, s[22:23]
	s_or_b64 s[64:65], vcc, s[24:25]
	s_or_b64 s[66:67], vcc, s[26:27]
	s_or_b64 s[74:75], vcc, s[28:29]
	s_or_b64 s[80:81], vcc, s[30:31]
	s_or_b64 s[96:97], vcc, s[34:35]
	v_cndmask_b32_e64 v197, v197, 0, s[40:41]
	v_cndmask_b32_e64 v179, v179, 0, s[40:41]
	v_cndmask_b32_e64 v195, 0, v195, s[4:5]
	v_cndmask_b32_e64 v180, 0, v180, s[4:5]
	v_cndmask_b32_e64 v195, v195, 0, vcc
	v_cndmask_b32_e64 v180, v180, 0, vcc
	v_cndmask_b32_e64 v194, v194, 0, s[46:47]
	v_cndmask_b32_e64 v165, v165, 0, s[46:47]
	v_cndmask_b32_e64 v193, v193, 0, s[48:49]
	v_cndmask_b32_e64 v166, v166, 0, s[48:49]
	v_cndmask_b32_e64 v192, v192, 0, s[50:51]
	v_cndmask_b32_e64 v167, v167, 0, s[50:51]
	v_cndmask_b32_e64 v191, v191, 0, s[52:53]
	v_cndmask_b32_e64 v168, v168, 0, s[52:53]
	v_cndmask_b32_e64 v190, v190, 0, s[54:55]
	v_cndmask_b32_e64 v169, v169, 0, s[54:55]
	v_cndmask_b32_e64 v189, v189, 0, s[56:57]
	v_cndmask_b32_e64 v170, v170, 0, s[56:57]
	v_cndmask_b32_e64 v188, v188, 0, s[58:59]
	v_cndmask_b32_e64 v171, v171, 0, s[58:59]
	v_cndmask_b32_e64 v187, v187, 0, s[60:61]
	v_cndmask_b32_e64 v172, v172, 0, s[60:61]
	v_cndmask_b32_e64 v186, v186, 0, s[62:63]
	v_cndmask_b32_e64 v173, v173, 0, s[62:63]
	v_cndmask_b32_e64 v185, v185, 0, s[64:65]
	v_cndmask_b32_e64 v174, v174, 0, s[64:65]
	v_cndmask_b32_e64 v184, v184, 0, s[66:67]
	v_cndmask_b32_e64 v175, v175, 0, s[66:67]
	v_cndmask_b32_e64 v183, v183, 0, s[74:75]
	v_cndmask_b32_e64 v176, v176, 0, s[74:75]
	v_cndmask_b32_e64 v182, v182, 0, s[80:81]
	v_cndmask_b32_e64 v177, v177, 0, s[80:81]
	v_cndmask_b32_e64 v181, v181, 0, s[96:97]
	v_cndmask_b32_e64 v178, v178, 0, s[96:97]

; DI f32x4 mfma16(bf16x8 a, bf16x8 b, f32x4 c) { return __builtin_amdgcn_mfma_f32_16x16x32_bf16(a, b, c, 0, 0, 0); }
; DI void flash_s3(const u16* sK, const bf16x8 (&qf)[2][2], float si0, float si1, f32x4 (&s)[2][4], int lane) {
;   const int l15 = lane & 15, lg = lane >> 4;
;   bf16x8 kf[4][2];
; #pragma unroll
;   for (int kt = 0; kt < 4; ++kt)
; #pragma unroll
;     for (int ks = 0; ks < 2; ++ks) kf[kt][ks] = *(const bf16x8*)(sK + (16 * kt + l15) * 72 + ks * 32 + lg * 8);
; #pragma unroll
;   for (int qt = 0; qt < 2; ++qt) {
;     const float si = qt ? si1 : si0;
; #pragma unroll
;     for (int kt = 0; kt < 4; ++kt) {
;       s[qt][kt] = f32x4{si, si, si, si};
; #pragma unroll
;       for (int ks = 0; ks < 2; ++ks) s[qt][kt] = mfma16(kf[kt][ks], qf[qt][ks], s[qt][kt]);
;     }
;   }
; }
; template <bool MASKED, class MaskF>
; DI void flash_pv3(const u16* sV, const f32x4 (&s)[2][4], f32x4 (&O)[2][4], float (&l)[2], MaskF ok, int lane) {
;   const int l15 = lane & 15, lg = lane >> 4;
;   union PFrag { unsigned u[4]; bf16x8 v; };
;   PFrag pf[2][2];
; #pragma unroll
;   for (int qt = 0; qt < 2; ++qt) {
;     float pr[4][4];
;     float rs = 0.f;
; #pragma unroll
;     for (int kt = 0; kt < 4; ++kt)
; #pragma unroll
;       for (int i = 0; i < 4; ++i) {
;         float pv = __builtin_amdgcn_exp2f(s[qt][kt][i]);
;         if (MASKED) pv = ok(kt, i) ? pv : 0.f;
;         pr[kt][i] = pv;
;         rs += pv;
;       }
;     l[qt] += rs;
; #pragma unroll
;     for (int ks2 = 0; ks2 < 2; ++ks2) {
;       pf[qt][ks2].u[0] = pk2(pr[2 * ks2][0], pr[2 * ks2][1]);
;       pf[qt][ks2].u[1] = pk2(pr[2 * ks2][2], pr[2 * ks2][3]);
;       pf[qt][ks2].u[2] = pk2(pr[2 * ks2 + 1][0], pr[2 * ks2 + 1][1]);
;       pf[qt][ks2].u[3] = pk2(pr[2 * ks2 + 1][2], pr[2 * ks2 + 1][3]);
;     }
;   }
; #pragma unroll
;   for (int ks2 = 0; ks2 < 2; ++ks2) {
; #pragma unroll
;     for (int dt = 0; dt < 4; ++dt) {
;       union { uint2 h[2]; bf16x8 v; } vf;
;       vf.h[0] = *(const uint2*)(sV + (16 * dt + l15) * 72 + 32 * ks2 + 4 * lg);
;       vf.h[1] = *(const uint2*)(sV + (16 * dt + l15) * 72 + 32 * ks2 + 16 + 4 * lg);
;       O[0][dt] = mfma16(vf.v, pf[0][ks2].v, O[0][dt]);
;       O[1][dt] = mfma16(vf.v, pf[1][ks2].v, O[1][dt]);
;     }
;   }
.Lmy_selC_old882:
	s_cmp_eq_u32 s32, 0
	s_cbranch_scc1 .LBB0_882
	v_mov_b64_e32 v[108:109], v[96:97]
	v_mov_b64_e32 v[112:113], v[92:93]
	v_mov_b64_e32 v[116:117], v[88:89]
	v_mov_b64_e32 v[128:129], v[84:85]
	v_mov_b64_e32 v[124:125], v[80:81]
	v_mov_b64_e32 v[120:121], v[76:77]
	v_mov_b64_e32 v[104:105], v[72:73]
	v_mov_b64_e32 v[100:101], v[68:69]
	v_mov_b64_e32 v[106:107], v[94:95]
	v_mov_b64_e32 v[110:111], v[90:91]
	v_mov_b64_e32 v[114:115], v[86:87]
	v_mov_b64_e32 v[126:127], v[82:83]
	v_mov_b64_e32 v[122:123], v[78:79]
	v_mov_b64_e32 v[118:119], v[74:75]
	v_mov_b64_e32 v[102:103], v[70:71]
	v_mov_b64_e32 v[98:99], v[66:67]
	s_branch .LBB0_882
.Lmy_selC_disp:
	s_cmp_eq_u32 s32, 0
	s_cbranch_scc0 .Lmy_selC_fastB
.Lmy_selC_fastA:
	v_lshrrev_b64 v[186:187], s42, v[20:21]
	v_lshrrev_b64 v[2:3], v2, v[22:23]
	v_cndmask_b32_e64 v0, v2, v186, s[36:37]
	v_and_b32_e32 v0, 1, v0
	s_mul_i32 s36, s44, 0x4800
	v_cmp_eq_u32_e32 vcc, 1, v0
	v_add_u32_e32 v0, s36, v158
	v_lshl_add_u32 v2, v28, 1, v0
	ds_read_b128 v[82:85], v2
	ds_read_b128 v[86:89], v2 offset:64
	s_cmp_eq_u32 s42, s33
	ds_read_b128 v[90:93], v2 offset:2304
	ds_read_b128 v[94:97], v2 offset:2368
	s_cselect_b64 s[36:37], -1, 0
	s_or_b64 s[36:37], vcc, s[36:37]
	v_cndmask_b32_e64 v78, v148, -v29, s[36:37]
	v_lshl_add_u32 v0, v164, 1, v0
	v_cndmask_b32_e64 v182, v148, -v161, s[36:37]
	ds_read_b128 v[166:169], v2 offset:4608
	ds_read_b128 v[170:173], v2 offset:4672
	ds_read_b128 v[174:177], v0
	ds_read_b128 v[178:181], v0 offset:64
	v_mov_b32_e32 v79, v78
	v_mov_b32_e32 v80, v78
	v_mov_b32_e32 v81, v78
	v_mov_b32_e32 v183, v182
	v_mov_b32_e32 v184, v182
	v_mov_b32_e32 v185, v182
	s_mulk_i32 s45, 0x4800
	v_lshlrev_b32_e32 v160, 1, v28
	v_lshlrev_b32_e32 v3, 1, v164
	s_add_i32 s40, s45, 32
	v_add3_u32 v198, s40, v160, v159
	v_add3_u32 v206, s40, v3, v159
	v_add_u32_e32 v214, 0x2000, v198
	v_add_u32_e32 v215, 0x2800, v198
	v_add_u32_e32 v216, 0x3000, v198
	v_add_u32_e32 v217, 0x2000, v206
	v_exp_f32_e32 v98, v98
	v_exp_f32_e32 v99, v99
	v_exp_f32_e32 v100, v100
	v_exp_f32_e32 v101, v101
	v_exp_f32_e32 v102, v102
	v_exp_f32_e32 v103, v103
	s_waitcnt lgkmcnt(7)
	v_mfma_f32_16x16x32_bf16 v[66:69], v[82:85], v[4:7], v[78:81]
	v_exp_f32_e32 v104, v104
	v_mfma_f32_16x16x32_bf16 v[82:85], v[82:85], v[12:15], v[182:185]
	v_exp_f32_e32 v105, v105
	s_waitcnt lgkmcnt(6)
	v_mfma_f32_16x16x32_bf16 v[66:69], v[86:89], v[8:11], v[66:69]
	ds_read_b64 v[198:199], v214 offset:1024
	ds_read_b64 v[200:201], v214 offset:1056
	ds_read_b64 v[202:203], v215 offset:1280
	ds_read_b64 v[204:205], v215 offset:1312
	ds_read_b64 v[206:207], v216 offset:1536
	ds_read_b64 v[208:209], v216 offset:1568
	ds_read_b64 v[210:211], v217 offset:1024
	ds_read_b64 v[212:213], v217 offset:1056
	v_exp_f32_e32 v118, v118
	v_exp_f32_e32 v119, v119
	s_waitcnt lgkmcnt(13)
	v_mfma_f32_16x16x32_bf16 v[70:73], v[90:93], v[4:7], v[78:81]
	v_exp_f32_e32 v120, v120
	v_mfma_f32_16x16x32_bf16 v[82:85], v[86:89], v[16:19], v[82:85]
	v_exp_f32_e32 v121, v121
	v_mfma_f32_16x16x32_bf16 v[86:89], v[90:93], v[12:15], v[182:185]
	v_exp_f32_e32 v122, v122
	v_exp_f32_e32 v123, v123
	s_waitcnt lgkmcnt(12)
	v_mfma_f32_16x16x32_bf16 v[70:73], v[94:97], v[8:11], v[70:73]
	v_exp_f32_e32 v124, v124
	v_exp_f32_e32 v125, v125
	s_waitcnt lgkmcnt(11)
	v_mfma_f32_16x16x32_bf16 v[74:77], v[166:169], v[4:7], v[78:81]
	v_exp_f32_e32 v126, v126
	v_exp_f32_e32 v127, v127
	s_waitcnt lgkmcnt(9)
	v_mfma_f32_16x16x32_bf16 v[78:81], v[174:177], v[4:7], v[78:81]
	v_exp_f32_e32 v128, v128
	v_mfma_f32_16x16x32_bf16 v[86:89], v[94:97], v[16:19], v[86:89]
	v_exp_f32_e32 v129, v129
	v_mfma_f32_16x16x32_bf16 v[90:93], v[166:169], v[12:15], v[182:185]
	v_exp_f32_e32 v114, v114
	v_mfma_f32_16x16x32_bf16 v[94:97], v[174:177], v[12:15], v[182:185]
	v_exp_f32_e32 v115, v115
	v_mfma_f32_16x16x32_bf16 v[74:77], v[170:173], v[8:11], v[74:77]
	v_exp_f32_e32 v116, v116
	v_exp_f32_e32 v117, v117
	s_waitcnt lgkmcnt(8)
	v_mfma_f32_16x16x32_bf16 v[78:81], v[178:181], v[8:11], v[78:81]
	v_exp_f32_e32 v110, v110
	v_exp_f32_e32 v111, v111
	v_mfma_f32_16x16x32_bf16 v[90:93], v[170:173], v[16:19], v[90:93]
	v_exp_f32_e32 v112, v112
	v_exp_f32_e32 v113, v113
	v_mfma_f32_16x16x32_bf16 v[94:97], v[178:181], v[16:19], v[94:97]
	v_exp_f32_e32 v106, v106
	v_exp_f32_e32 v107, v107
	v_exp_f32_e32 v108, v108
	v_exp_f32_e32 v109, v109
	ds_read_b64 v[166:167], v214 offset:1088
	ds_read_b64 v[168:169], v214 offset:1120
	ds_read_b64 v[170:171], v215 offset:1344
	ds_read_b64 v[172:173], v215 offset:1376
	ds_read_b64 v[174:175], v216 offset:1600
	ds_read_b64 v[176:177], v216 offset:1632
	ds_read_b64 v[178:179], v217 offset:1088
	ds_read_b64 v[180:181], v217 offset:1120
	v_cvt_pk_bf16_f32 v186, v98, v99
	v_cvt_pk_bf16_f32 v187, v100, v101
	v_cvt_pk_bf16_f32 v188, v102, v103
	v_cvt_pk_bf16_f32 v189, v104, v105
	v_cvt_pk_bf16_f32 v190, v126, v127
	v_cvt_pk_bf16_f32 v191, v128, v129
	v_cvt_pk_bf16_f32 v192, v114, v115
	v_cvt_pk_bf16_f32 v193, v116, v117
	v_cvt_pk_bf16_f32 v194, v118, v119
	v_cvt_pk_bf16_f32 v195, v120, v121
	v_cvt_pk_bf16_f32 v196, v122, v123
	v_cvt_pk_bf16_f32 v197, v124, v125
	v_cvt_pk_bf16_f32 v182, v110, v111
	v_cvt_pk_bf16_f32 v183, v112, v113
	v_cvt_pk_bf16_f32 v184, v106, v107
	v_cvt_pk_bf16_f32 v185, v108, v109
	s_waitcnt lgkmcnt(14)
	v_mfma_f32_16x16x32_bf16 v[58:61], v[198:201], v[186:189], v[58:61]
	v_add_f32_e32 v0, 0, v98
	v_add_f32_e32 v2, 0, v126
	v_mfma_f32_16x16x32_bf16 v[42:45], v[198:201], v[190:193], v[42:45]
	v_add_f32_e32 v0, v99, v0
	v_add_f32_e32 v2, v127, v2
	s_waitcnt lgkmcnt(12)
; DI f32x4 mfma16(bf16x8 a, bf16x8 b, f32x4 c) { return __builtin_amdgcn_mfma_f32_16x16x32_bf16(a, b, c, 0, 0, 0); }
; template <bool MASKED, class MaskF>
; DI void flash_pv3(const u16* sV, const f32x4 (&s)[2][4], f32x4 (&O)[2][4], float (&l)[2], MaskF ok, int lane) {
;     ...
;     l[qt] += rs;
; #pragma unroll
;     for (int ks2 = 0; ks2 < 2; ++ks2) {
;       pf[qt][ks2].u[0] = pk2(pr[2 * ks2][0], pr[2 * ks2][1]);
;       pf[qt][ks2].u[1] = pk2(pr[2 * ks2][2], pr[2 * ks2][3]);
;       pf[qt][ks2].u[2] = pk2(pr[2 * ks2 + 1][0], pr[2 * ks2 + 1][1]);
;       pf[qt][ks2].u[3] = pk2(pr[2 * ks2 + 1][2], pr[2 * ks2 + 1][3]);
;     }
;   }
; #pragma unroll
;   for (int ks2 = 0; ks2 < 2; ++ks2) {
; #pragma unroll
;     for (int dt = 0; dt < 4; ++dt) {
;       union { uint2 h[2]; bf16x8 v; } vf;
;       vf.h[0] = *(const uint2*)(sV + (16 * dt + l15) * 72 + 32 * ks2 + 4 * lg);
;       vf.h[1] = *(const uint2*)(sV + (16 * dt + l15) * 72 + 32 * ks2 + 16 + 4 * lg);
;       O[0][dt] = mfma16(vf.v, pf[0][ks2].v, O[0][dt]);
;       O[1][dt] = mfma16(vf.v, pf[1][ks2].v, O[1][dt]);
;     }
;   }
	v_mfma_f32_16x16x32_bf16 v[54:57], v[202:205], v[186:189], v[54:57]
	v_add_f32_e32 v0, v100, v0
	v_add_f32_e32 v2, v128, v2
	v_mfma_f32_16x16x32_bf16 v[38:41], v[202:205], v[190:193], v[38:41]
	v_add_f32_e32 v0, v101, v0
	v_add_f32_e32 v2, v129, v2
	s_waitcnt lgkmcnt(10)
	v_mfma_f32_16x16x32_bf16 v[50:53], v[206:209], v[186:189], v[50:53]
	v_add_f32_e32 v0, v102, v0
	v_add_f32_e32 v2, v114, v2
	v_mfma_f32_16x16x32_bf16 v[34:37], v[206:209], v[190:193], v[34:37]
	v_add_f32_e32 v0, v103, v0
	v_add_f32_e32 v2, v115, v2
	s_waitcnt lgkmcnt(8)
	v_mfma_f32_16x16x32_bf16 v[46:49], v[210:213], v[186:189], v[46:49]
	v_add_f32_e32 v0, v104, v0
	v_add_f32_e32 v2, v116, v2
	v_mfma_f32_16x16x32_bf16 v[30:33], v[210:213], v[190:193], v[30:33]
	v_add_f32_e32 v0, v105, v0
	v_add_f32_e32 v2, v117, v2
	s_waitcnt lgkmcnt(6)
	v_mfma_f32_16x16x32_bf16 v[58:61], v[166:169], v[194:197], v[58:61]
	v_add_f32_e32 v0, v118, v0
	v_add_f32_e32 v2, v110, v2
	v_mfma_f32_16x16x32_bf16 v[42:45], v[166:169], v[182:185], v[42:45]
	v_add_f32_e32 v0, v119, v0
	v_add_f32_e32 v2, v111, v2
	s_waitcnt lgkmcnt(4)
	v_mfma_f32_16x16x32_bf16 v[54:57], v[170:173], v[194:197], v[54:57]
	v_add_f32_e32 v0, v120, v0
	v_add_f32_e32 v2, v112, v2
	v_mfma_f32_16x16x32_bf16 v[38:41], v[170:173], v[182:185], v[38:41]
	v_add_f32_e32 v0, v121, v0
	v_add_f32_e32 v2, v113, v2
	s_waitcnt lgkmcnt(2)
	v_mfma_f32_16x16x32_bf16 v[50:53], v[174:177], v[194:197], v[50:53]
	v_add_f32_e32 v0, v122, v0
	v_add_f32_e32 v2, v106, v2
	v_mfma_f32_16x16x32_bf16 v[34:37], v[174:177], v[182:185], v[34:37]
	v_add_f32_e32 v0, v123, v0
	v_add_f32_e32 v2, v107, v2
	s_waitcnt lgkmcnt(0)
	v_mfma_f32_16x16x32_bf16 v[46:49], v[178:181], v[194:197], v[46:49]
	v_add_f32_e32 v0, v124, v0
	v_add_f32_e32 v2, v108, v2
	v_mfma_f32_16x16x32_bf16 v[30:33], v[178:181], v[182:185], v[30:33]
	v_add_f32_e32 v0, v125, v0
	v_add_f32_e32 v2, v109, v2
	v_add_f32_e32 v163, v163, v0
	v_add_f32_e32 v162, v162, v2
	s_mov_b32 s32, 1
	s_branch .LBB0_888
; DI f32x4 mfma16(bf16x8 a, bf16x8 b, f32x4 c) { return __builtin_amdgcn_mfma_f32_16x16x32_bf16(a, b, c, 0, 0, 0); }
; DI void flash_s3(const u16* sK, const bf16x8 (&qf)[2][2], float si0, float si1, f32x4 (&s)[2][4], int lane) {
;   const int l15 = lane & 15, lg = lane >> 4;
;   bf16x8 kf[4][2];
; #pragma unroll
;   for (int kt = 0; kt < 4; ++kt)
; #pragma unroll
;     for (int ks = 0; ks < 2; ++ks) kf[kt][ks] = *(const bf16x8*)(sK + (16 * kt + l15) * 72 + ks * 32 + lg * 8);
; #pragma unroll
;   for (int qt = 0; qt < 2; ++qt) {
;     const float si = qt ? si1 : si0;
; #pragma unroll
;     for (int kt = 0; kt < 4; ++kt) {
;       s[qt][kt] = f32x4{si, si, si, si};
; #pragma unroll
;       for (int ks = 0; ks < 2; ++ks) s[qt][kt] = mfma16(kf[kt][ks], qf[qt][ks], s[qt][kt]);
;     }
;   }
; }
; template <bool MASKED, class MaskF>
; DI void flash_pv3(const u16* sV, const f32x4 (&s)[2][4], f32x4 (&O)[2][4], float (&l)[2], MaskF ok, int lane) {
;   const int l15 = lane & 15, lg = lane >> 4;
;   union PFrag { unsigned u[4]; bf16x8 v; };
;   PFrag pf[2][2];
; #pragma unroll
;   for (int qt = 0; qt < 2; ++qt) {
;     float pr[4][4];
;     float rs = 0.f;
; #pragma unroll
;     for (int kt = 0; kt < 4; ++kt)
; #pragma unroll
;       for (int i = 0; i < 4; ++i) {
;         float pv = __builtin_amdgcn_exp2f(s[qt][kt][i]);
;         if (MASKED) pv = ok(kt, i) ? pv : 0.f;
;         pr[kt][i] = pv;
;         rs += pv;
;       }
;     l[qt] += rs;
; #pragma unroll
;     for (int ks2 = 0; ks2 < 2; ++ks2) {
;       pf[qt][ks2].u[0] = pk2(pr[2 * ks2][0], pr[2 * ks2][1]);
;       pf[qt][ks2].u[1] = pk2(pr[2 * ks2][2], pr[2 * ks2][3]);
;       pf[qt][ks2].u[2] = pk2(pr[2 * ks2 + 1][0], pr[2 * ks2 + 1][1]);
;       pf[qt][ks2].u[3] = pk2(pr[2 * ks2 + 1][2], pr[2 * ks2 + 1][3]);
;     }
;   }
; #pragma unroll
;   for (int ks2 = 0; ks2 < 2; ++ks2) {
; #pragma unroll
;     for (int dt = 0; dt < 4; ++dt) {
;       union { uint2 h[2]; bf16x8 v; } vf;
;       vf.h[0] = *(const uint2*)(sV + (16 * dt + l15) * 72 + 32 * ks2 + 4 * lg);
;       vf.h[1] = *(const uint2*)(sV + (16 * dt + l15) * 72 + 32 * ks2 + 16 + 4 * lg);
;       O[0][dt] = mfma16(vf.v, pf[0][ks2].v, O[0][dt]);
;       O[1][dt] = mfma16(vf.v, pf[1][ks2].v, O[1][dt]);
;     }
;   }
.Lmy_selC_fastB:
	v_lshrrev_b64 v[186:187], s42, v[20:21]
	v_lshrrev_b64 v[2:3], v2, v[22:23]
	v_cndmask_b32_e64 v0, v2, v186, s[36:37]
	v_and_b32_e32 v0, 1, v0
	s_mul_i32 s36, s44, 0x4800
	v_cmp_eq_u32_e32 vcc, 1, v0
	v_add_u32_e32 v0, s36, v158
	v_lshl_add_u32 v2, v28, 1, v0
	ds_read_b128 v[126:129], v2
	ds_read_b128 v[114:117], v2 offset:64
	s_cmp_eq_u32 s42, s33
	ds_read_b128 v[110:113], v2 offset:2304
	ds_read_b128 v[106:109], v2 offset:2368
	s_cselect_b64 s[36:37], -1, 0
	s_or_b64 s[36:37], vcc, s[36:37]
	v_cndmask_b32_e64 v122, v148, -v29, s[36:37]
	v_lshl_add_u32 v0, v164, 1, v0
	v_cndmask_b32_e64 v182, v148, -v161, s[36:37]
	ds_read_b128 v[166:169], v2 offset:4608
	ds_read_b128 v[170:173], v2 offset:4672
	ds_read_b128 v[174:177], v0
	ds_read_b128 v[178:181], v0 offset:64
	v_mov_b32_e32 v123, v122
	v_mov_b32_e32 v124, v122
	v_mov_b32_e32 v125, v122
	v_mov_b32_e32 v183, v182
	v_mov_b32_e32 v184, v182
	v_mov_b32_e32 v185, v182
	s_mulk_i32 s45, 0x4800
	v_lshlrev_b32_e32 v160, 1, v28
	v_lshlrev_b32_e32 v3, 1, v164
	s_add_i32 s40, s45, 32
	v_add3_u32 v198, s40, v160, v159
	v_add3_u32 v206, s40, v3, v159
	v_add_u32_e32 v214, 0x2000, v198
	v_add_u32_e32 v215, 0x2800, v198
	v_add_u32_e32 v216, 0x3000, v198
	v_add_u32_e32 v217, 0x2000, v206
	v_exp_f32_e32 v66, v66
	v_exp_f32_e32 v67, v67
	v_exp_f32_e32 v68, v68
	v_exp_f32_e32 v69, v69
	v_exp_f32_e32 v70, v70
	v_exp_f32_e32 v71, v71
	s_waitcnt lgkmcnt(7)
	v_mfma_f32_16x16x32_bf16 v[98:101], v[126:129], v[4:7], v[122:125]
	v_exp_f32_e32 v72, v72
	v_mfma_f32_16x16x32_bf16 v[126:129], v[126:129], v[12:15], v[182:185]
	v_exp_f32_e32 v73, v73
	s_waitcnt lgkmcnt(6)
	v_mfma_f32_16x16x32_bf16 v[98:101], v[114:117], v[8:11], v[98:101]
	ds_read_b64 v[198:199], v214 offset:1024
	ds_read_b64 v[200:201], v214 offset:1056
	ds_read_b64 v[202:203], v215 offset:1280
	ds_read_b64 v[204:205], v215 offset:1312
	ds_read_b64 v[206:207], v216 offset:1536
	ds_read_b64 v[208:209], v216 offset:1568
	ds_read_b64 v[210:211], v217 offset:1024
	ds_read_b64 v[212:213], v217 offset:1056
	v_exp_f32_e32 v74, v74
	v_exp_f32_e32 v75, v75
	s_waitcnt lgkmcnt(13)
	v_mfma_f32_16x16x32_bf16 v[102:105], v[110:113], v[4:7], v[122:125]
	v_exp_f32_e32 v76, v76
	v_mfma_f32_16x16x32_bf16 v[126:129], v[114:117], v[16:19], v[126:129]
	v_exp_f32_e32 v77, v77
	v_mfma_f32_16x16x32_bf16 v[114:117], v[110:113], v[12:15], v[182:185]
	v_exp_f32_e32 v78, v78
	v_exp_f32_e32 v79, v79
	s_waitcnt lgkmcnt(12)
	v_mfma_f32_16x16x32_bf16 v[102:105], v[106:109], v[8:11], v[102:105]
	v_exp_f32_e32 v80, v80
	v_exp_f32_e32 v81, v81
	s_waitcnt lgkmcnt(11)
	v_mfma_f32_16x16x32_bf16 v[118:121], v[166:169], v[4:7], v[122:125]
	v_exp_f32_e32 v82, v82
	v_exp_f32_e32 v83, v83
	s_waitcnt lgkmcnt(9)
	v_mfma_f32_16x16x32_bf16 v[122:125], v[174:177], v[4:7], v[122:125]
	v_exp_f32_e32 v84, v84
	v_mfma_f32_16x16x32_bf16 v[114:117], v[106:109], v[16:19], v[114:117]
	v_exp_f32_e32 v85, v85
	v_mfma_f32_16x16x32_bf16 v[110:113], v[166:169], v[12:15], v[182:185]
	v_exp_f32_e32 v86, v86
	v_mfma_f32_16x16x32_bf16 v[106:109], v[174:177], v[12:15], v[182:185]
	v_exp_f32_e32 v87, v87
	v_mfma_f32_16x16x32_bf16 v[118:121], v[170:173], v[8:11], v[118:121]
	v_exp_f32_e32 v88, v88
	v_exp_f32_e32 v89, v89
	s_waitcnt lgkmcnt(8)
	v_mfma_f32_16x16x32_bf16 v[122:125], v[178:181], v[8:11], v[122:125]
	v_exp_f32_e32 v90, v90
	v_exp_f32_e32 v91, v91
	v_mfma_f32_16x16x32_bf16 v[110:113], v[170:173], v[16:19], v[110:113]
	v_exp_f32_e32 v92, v92
	v_exp_f32_e32 v93, v93
	v_mfma_f32_16x16x32_bf16 v[106:109], v[178:181], v[16:19], v[106:109]
	v_exp_f32_e32 v94, v94
	v_exp_f32_e32 v95, v95
	v_exp_f32_e32 v96, v96
	v_exp_f32_e32 v97, v97
	ds_read_b64 v[166:167], v214 offset:1088
	ds_read_b64 v[168:169], v214 offset:1120
	ds_read_b64 v[170:171], v215 offset:1344
	ds_read_b64 v[172:173], v215 offset:1376
	ds_read_b64 v[174:175], v216 offset:1600
	ds_read_b64 v[176:177], v216 offset:1632
	ds_read_b64 v[178:179], v217 offset:1088
	ds_read_b64 v[180:181], v217 offset:1120
	v_cvt_pk_bf16_f32 v186, v66, v67
	v_cvt_pk_bf16_f32 v187, v68, v69
	v_cvt_pk_bf16_f32 v188, v70, v71
	v_cvt_pk_bf16_f32 v189, v72, v73
	v_cvt_pk_bf16_f32 v190, v82, v83
	v_cvt_pk_bf16_f32 v191, v84, v85
	v_cvt_pk_bf16_f32 v192, v86, v87
	v_cvt_pk_bf16_f32 v193, v88, v89
	v_cvt_pk_bf16_f32 v194, v74, v75
	v_cvt_pk_bf16_f32 v195, v76, v77
	v_cvt_pk_bf16_f32 v196, v78, v79
	v_cvt_pk_bf16_f32 v197, v80, v81
	v_cvt_pk_bf16_f32 v182, v90, v91
	v_cvt_pk_bf16_f32 v183, v92, v93
	v_cvt_pk_bf16_f32 v184, v94, v95
	v_cvt_pk_bf16_f32 v185, v96, v97
	s_waitcnt lgkmcnt(14)
	v_mfma_f32_16x16x32_bf16 v[58:61], v[198:201], v[186:189], v[58:61]
	v_add_f32_e32 v0, 0, v66
	v_add_f32_e32 v2, 0, v82
	v_mfma_f32_16x16x32_bf16 v[42:45], v[198:201], v[190:193], v[42:45]
	v_add_f32_e32 v0, v67, v0
	v_add_f32_e32 v2, v83, v2
	s_waitcnt lgkmcnt(12)
	v_mfma_f32_16x16x32_bf16 v[54:57], v[202:205], v[186:189], v[54:57]
	v_add_f32_e32 v0, v68, v0
	v_add_f32_e32 v2, v84, v2
	v_mfma_f32_16x16x32_bf16 v[38:41], v[202:205], v[190:193], v[38:41]
	v_add_f32_e32 v0, v69, v0
	v_add_f32_e32 v2, v85, v2
	s_waitcnt lgkmcnt(10)
	v_mfma_f32_16x16x32_bf16 v[50:53], v[206:209], v[186:189], v[50:53]
	v_add_f32_e32 v0, v70, v0
	v_add_f32_e32 v2, v86, v2
	v_mfma_f32_16x16x32_bf16 v[34:37], v[206:209], v[190:193], v[34:37]
	v_add_f32_e32 v0, v71, v0
	v_add_f32_e32 v2, v87, v2
	s_waitcnt lgkmcnt(8)
	v_mfma_f32_16x16x32_bf16 v[46:49], v[210:213], v[186:189], v[46:49]
	v_add_f32_e32 v0, v72, v0
	v_add_f32_e32 v2, v88, v2
	v_mfma_f32_16x16x32_bf16 v[30:33], v[210:213], v[190:193], v[30:33]
	v_add_f32_e32 v0, v73, v0
	v_add_f32_e32 v2, v89, v2
	s_waitcnt lgkmcnt(6)
	v_mfma_f32_16x16x32_bf16 v[58:61], v[166:169], v[194:197], v[58:61]
	v_add_f32_e32 v0, v74, v0
	v_add_f32_e32 v2, v90, v2
	v_mfma_f32_16x16x32_bf16 v[42:45], v[166:169], v[182:185], v[42:45]
	v_add_f32_e32 v0, v75, v0
	v_add_f32_e32 v2, v91, v2
	s_waitcnt lgkmcnt(4)
	v_mfma_f32_16x16x32_bf16 v[54:57], v[170:173], v[194:197], v[54:57]
	v_add_f32_e32 v0, v76, v0
	v_add_f32_e32 v2, v92, v2
	v_mfma_f32_16x16x32_bf16 v[38:41], v[170:173], v[182:185], v[38:41]
	v_add_f32_e32 v0, v77, v0
	v_add_f32_e32 v2, v93, v2
	s_waitcnt lgkmcnt(2)
	v_mfma_f32_16x16x32_bf16 v[50:53], v[174:177], v[194:197], v[50:53]
	v_add_f32_e32 v0, v78, v0
	v_add_f32_e32 v2, v94, v2
	v_mfma_f32_16x16x32_bf16 v[34:37], v[174:177], v[182:185], v[34:37]
	v_add_f32_e32 v0, v79, v0
	v_add_f32_e32 v2, v95, v2
	s_waitcnt lgkmcnt(0)
	v_mfma_f32_16x16x32_bf16 v[46:49], v[178:181], v[194:197], v[46:49]
	v_add_f32_e32 v0, v80, v0
	v_add_f32_e32 v2, v96, v2
	v_mfma_f32_16x16x32_bf16 v[30:33], v[178:181], v[182:185], v[30:33]
	v_add_f32_e32 v0, v81, v0
	v_add_f32_e32 v2, v97, v2
	v_add_f32_e32 v163, v163, v0
	v_add_f32_e32 v162, v162, v2
	s_mov_b32 s32, 0
	s_branch .LBB0_888

; #define MAKE_RSRC(PTR) __builtin_amdgcn_make_buffer_rsrc((void*)(PTR), 0, 0x7fffffff, 0x00020000)
; #define ISSUE_TILE(RK, RV, T, LDV)                                                   \
;   {                                                                                  \
;     pk0 = BLOAD(RK, koff, (T)*8192);                                                 \
;     pv0 = BLOAD(RV, ((LDV) == 512) ? voffc : voffs, (T)*128);                        \
;   }
; DI void nsa_item(int wv0, PP p, int item, unsigned char* smem) {
;     ...
; #pragma unroll
;   for (int qt = 0; qt < 2; ++qt) {
;     float s = l[qt];
;     s += __shfl_xor(s, 16);
;     s += __shfl_xor(s, 32);
;     const float sc = NGb[ngoff + qt * 3 + 1] / s;
; #pragma unroll
;     for (int dt = 0; dt < 4; ++dt) {
;       float4* a = (float4*)(ACCb + (aoff + qt * 64 + 16 * dt));
;       float4 o = *a;
;       o.x += O[qt][dt][0] * sc; o.y += O[qt][dt][1] * sc; o.z += O[qt][dt][2] * sc; o.w += O[qt][dt][3] * sc;
;       *a = o;
;     }
;   }
;   RESET_STATE()
;   if (usefix) { m[0] = nb_w[0]; m[1] = nb_w[1]; }
;   {
;     const __amdgpu_buffer_rsrc_t rK = MAKE_RSRC((const u16*)(p->ws + OFF_KW) + (size_t)bg * S_ * 64);
;     const __amdgpu_buffer_rsrc_t rV = MAKE_RSRC((const u16*)(p->ws + OFF_VWT) + (size_t)bg * 64 * S_);
;     const int j0 = i >= 8 ? i - 8 : 0;
;     ISSUE_TILE(rK, rV, j0, S_)
;     COMMIT_BUF(0)
;     __syncthreads();
;     if (j0 + 1 <= i) ISSUE_TILE(rK, rV, j0 + 1, S_)
.LBB0_900:
	ds_bpermute_b32 v2, v144, v163
	v_or_b32_e32 v0, 1, v142
	s_lshl_b32 s2, s84, 19
	s_lshl_b32 s2, s2, 1
	v_readlane_b32 s3, v247, 63
	v_lshl_add_u64 v[22:23], v[0:1], 2, s[94:95]
	global_load_dword v200, v[22:23], off
	v_add_u32_e32 v0, 4, v142
	v_lshl_add_u64 v[22:23], v[0:1], 2, s[94:95]
	global_load_dword v201, v[22:23], off
	s_add_u32 s68, s3, s2
	v_readlane_b32 s3, v246, 0
	s_addc_u32 s3, s3, 0
	s_and_b32 s69, s3, 0xffff
	v_readlane_b32 s3, v246, 1
	s_add_u32 s72, s3, s2
	v_readlane_b32 s2, v246, 2
	s_addc_u32 s2, s2, 0
	s_and_b32 s73, s2, 0xffff
	s_sub_i32 s2, 0x77, s88
	s_cmpk_lt_i32 s88, 0x78
	s_cselect_b32 s2, s2, 0
	s_mov_b32 s74, s70
	s_mov_b32 s75, s71
	s_lshl_b32 s3, s2, 13
	s_lshl_b32 s6, s2, 7
	buffer_load_dwordx4 v[202:205], v152, s[68:71], s3 offen
	buffer_load_dwordx4 v[206:209], v143, s[72:75], s6 offen
	s_waitcnt lgkmcnt(0)
	v_add_f32_e32 v2, v163, v2
	ds_bpermute_b32 v3, v145, v2
	s_waitcnt lgkmcnt(0)
	v_add_f32_e32 v20, v2, v3
	s_waitcnt vmcnt(0)
	v_div_scale_f32 v2, s[4:5], v20, v20, v200
	v_rcp_f32_e32 v3, v2
	s_nop 0
	v_fma_f32 v21, -v2, v3, 1.0
	v_fmac_f32_e32 v3, v21, v3
	v_div_scale_f32 v21, vcc, v200, v20, v200
	v_mul_f32_e32 v22, v21, v3
	v_fma_f32 v23, -v2, v22, v21
	v_fmac_f32_e32 v22, v23, v3
	v_fma_f32 v2, -v2, v22, v21
	v_div_fmas_f32 v2, v2, v3, v22
	v_div_fixup_f32 v0, v2, v20, v200
	v_pk_fma_f32 v[218:219], v[58:59], v[0:1], v[218:219] op_sel_hi:[1,0,1]
	v_pk_fma_f32 v[220:221], v[60:61], v[0:1], v[220:221] op_sel_hi:[1,0,1]
	v_pk_fma_f32 v[222:223], v[54:55], v[0:1], v[222:223] op_sel_hi:[1,0,1]
	v_pk_fma_f32 v[224:225], v[56:57], v[0:1], v[224:225] op_sel_hi:[1,0,1]
	v_pk_fma_f32 v[226:227], v[50:51], v[0:1], v[226:227] op_sel_hi:[1,0,1]
	v_pk_fma_f32 v[228:229], v[52:53], v[0:1], v[228:229] op_sel_hi:[1,0,1]
	v_pk_fma_f32 v[230:231], v[46:47], v[0:1], v[230:231] op_sel_hi:[1,0,1]
	v_pk_fma_f32 v[232:233], v[48:49], v[0:1], v[232:233] op_sel_hi:[1,0,1]
	ds_bpermute_b32 v0, v144, v162
	s_waitcnt lgkmcnt(0)
	v_add_f32_e32 v0, v162, v0
	ds_bpermute_b32 v2, v145, v0
	s_waitcnt lgkmcnt(0)
	v_add_f32_e32 v20, v0, v2
	v_div_scale_f32 v2, s[4:5], v20, v20, v201
	v_rcp_f32_e32 v3, v2
	s_lshl_b32 s4, s2, 7
	s_cmp_ge_i32 s2, s33
	v_fma_f32 v21, -v2, v3, 1.0
	v_fmac_f32_e32 v3, v21, v3
	v_div_scale_f32 v21, vcc, v201, v20, v201
	v_mul_f32_e32 v22, v21, v3
	v_fma_f32 v23, -v2, v22, v21
	v_fmac_f32_e32 v22, v23, v3
	v_fma_f32 v2, -v2, v22, v21
	v_div_fmas_f32 v2, v2, v3, v22
	v_div_fixup_f32 v0, v2, v20, v201
	v_pk_fma_f32 v[234:235], v[42:43], v[0:1], v[234:235] op_sel_hi:[1,0,1]
	v_pk_fma_f32 v[236:237], v[44:45], v[0:1], v[236:237] op_sel_hi:[1,0,1]
	v_pk_fma_f32 v[238:239], v[38:39], v[0:1], v[238:239] op_sel_hi:[1,0,1]
	v_pk_fma_f32 v[240:241], v[40:41], v[0:1], v[240:241] op_sel_hi:[1,0,1]
	v_pk_fma_f32 v[242:243], v[34:35], v[0:1], v[242:243] op_sel_hi:[1,0,1]
	v_pk_fma_f32 v[244:245], v[36:37], v[0:1], v[244:245] op_sel_hi:[1,0,1]
	v_pk_fma_f32 v[248:249], v[30:31], v[0:1], v[248:249] op_sel_hi:[1,0,1]
	v_pk_fma_f32 v[250:251], v[32:33], v[0:1], v[250:251] op_sel_hi:[1,0,1]
	s_waitcnt vmcnt(1)
	ds_write_b128 v154, v[202:205]
	s_waitcnt vmcnt(0)
	ds_write_b128 v154, v[206:209] offset:9216
	s_waitcnt lgkmcnt(0)
	s_barrier
	s_cbranch_scc1 .LBB0_902
	s_add_i32 s5, s2, 1
	s_lshl_b32 s6, s5, 7
	s_lshl_b32 s5, s5, 13
	s_mov_b32 s74, s70
	s_mov_b32 s75, s71
	buffer_load_dwordx4 v[20:23], v152, s[68:71], s5 offen
	buffer_load_dwordx4 v[32:35], v143, s[72:75], s6 offen

; DI void phaseJ(int wv0, PP p) {
;   const int lane = my_tid(wv0) & 63;
;   const float* SS2 = (const float*)(p->ws + OFF_SS2);
;   for (int row = blockIdx.x * 8 + wv0; row < T_; row += gridDim.x * 8) {
;     float t = (lane < 16) ? SS2[(size_t)row * 16 + lane] : 0.f;
;     t = wave_sum(t);
;     const float rinv = rsqrtf(t * (1.f / 1024.f) + 1e-6f);
;     float4* xr = (float4*)(p->out + (size_t)row * 1024);
; #pragma unroll
;     for (int r = 0; r < 4; ++r) {
;       float4 v = xr[lane + 64 * r];
;       const float4 g = ((const float4*)p->g3)[lane + 64 * r];
;       v.x *= rinv * g.x; v.y *= rinv * g.y; v.z *= rinv * g.z; v.w *= rinv * g.w;
;       xr[lane + 64 * r] = v;
;     }
;   }
; }
.LBB0_1279:
	s_lshl_b32 s0, s94, 3
	s_add_i32 s10, s89, s0
	s_cmpk_gt_i32 s10, 0x7fff
	s_cbranch_scc1 .LBB0_1284
	s_load_dwordx4 s[4:7], s[8:9], 0xb8
	s_load_dwordx2 s[0:1], s[8:9], 0xc8
	v_and_b32_e32 v3, 63, v3
	v_lshlrev_b32_e32 v4, 2, v3
	v_mov_b32_e32 v5, 0
	v_xor_b32_e32 v6, 32, v2
	s_waitcnt lgkmcnt(0)
	v_lshl_add_u64 v[0:1], s[0:1], 0, v[4:5]
	v_and_b32_e32 v4, 0xffffffc0, v2
	v_add_u32_e32 v4, 64, v4
	v_cmp_lt_i32_e64 s[2:3], v6, v4
	v_xor_b32_e32 v7, 16, v2
	v_xor_b32_e32 v8, 8, v2
	v_cndmask_b32_e64 v6, v2, v6, s[2:3]
	v_cmp_lt_i32_e64 s[2:3], v7, v4
	v_xor_b32_e32 v9, 4, v2
	v_xor_b32_e32 v10, 2, v2
	v_cndmask_b32_e64 v7, v2, v7, s[2:3]
	v_cmp_lt_i32_e64 s[2:3], v8, v4
	s_mov_b64 s[0:1], 0x21d4100
	v_xor_b32_e32 v11, 1, v2
	v_cndmask_b32_e64 v8, v2, v8, s[2:3]
	v_cmp_lt_i32_e64 s[2:3], v9, v4
	v_lshl_add_u64 v[0:1], v[0:1], 0, s[0:1]
	v_cmp_lt_i32_e64 s[0:1], v11, v4
	v_cndmask_b32_e64 v9, v2, v9, s[2:3]
	v_cmp_lt_i32_e64 s[2:3], v10, v4
	v_lshlrev_b32_e32 v4, 4, v3
	v_cmp_gt_u32_e32 vcc, 16, v3
	v_cndmask_b32_e64 v10, v2, v10, s[2:3]
	s_load_dword s2, s[90:91], 0xd8
	v_cndmask_b32_e64 v2, v2, v11, s[0:1]
	v_lshlrev_b32_e32 v6, 2, v6
	v_lshlrev_b32_e32 v7, 2, v7
	v_lshlrev_b32_e32 v8, 2, v8
	v_lshlrev_b32_e32 v9, 2, v9
	v_lshlrev_b32_e32 v10, 2, v10
	v_lshlrev_b32_e32 v11, 2, v2
	s_waitcnt lgkmcnt(0)
	s_lshl_b32 s2, s2, 3
	v_lshl_add_u64 v[2:3], s[4:5], 0, v[4:5]
	v_lshl_add_u64 v[4:5], s[6:7], 0, v[4:5]
	v_mov_b32_e32 v12, 0x358637bd
	s_mov_b32 s3, 0x800000
	global_load_dwordx4 v[32:35], v[2:3], off
	global_load_dwordx4 v[36:39], v[2:3], off offset:1024
	global_load_dwordx4 v[40:43], v[2:3], off offset:2048
	global_load_dwordx4 v[44:47], v[2:3], off offset:3072
.Lmy_J_loop:
	s_mov_b32 s12, 0
	s_mov_b32 s13, s10
	s_mov_b32 s1, 0
	v_mov_b32_e32 v80, 0
	s_lshl_b32 s0, s13, 6
	v_lshl_add_u64 v[72:73], v[0:1], 0, s[0:1]
	s_lshl_b32 s0, s13, 12
	v_lshl_add_u64 v[64:65], v[4:5], 0, s[0:1]
	s_and_saveexec_b64 s[4:5], vcc
	global_load_dword v80, v[72:73], off
	s_or_b64 exec, exec, s[4:5]
	global_load_dwordx4 v[96:99], v[64:65], off
	global_load_dwordx4 v[100:103], v[64:65], off offset:1024
	global_load_dwordx4 v[104:107], v[64:65], off offset:2048
	global_load_dwordx4 v[108:111], v[64:65], off offset:3072
	s_add_i32 s12, s12, 1
	s_add_i32 s13, s13, s2
	s_cmp_lt_i32 s13, 0x8000
	s_cbranch_scc0 .Lmy_J_issued
	v_mov_b32_e32 v81, 0
	s_lshl_b32 s0, s13, 6
	v_lshl_add_u64 v[74:75], v[0:1], 0, s[0:1]
	s_lshl_b32 s0, s13, 12
	v_lshl_add_u64 v[66:67], v[4:5], 0, s[0:1]
	s_and_saveexec_b64 s[4:5], vcc
	global_load_dword v81, v[74:75], off
	s_or_b64 exec, exec, s[4:5]
	global_load_dwordx4 v[112:115], v[66:67], off
	global_load_dwordx4 v[116:119], v[66:67], off offset:1024
	global_load_dwordx4 v[120:123], v[66:67], off offset:2048
	global_load_dwordx4 v[124:127], v[66:67], off offset:3072
	s_add_i32 s12, s12, 1
	s_add_i32 s13, s13, s2
	s_cmp_lt_i32 s13, 0x8000
	s_cbranch_scc0 .Lmy_J_issued
	v_mov_b32_e32 v82, 0
	s_lshl_b32 s0, s13, 6
	v_lshl_add_u64 v[76:77], v[0:1], 0, s[0:1]
	s_lshl_b32 s0, s13, 12
	v_lshl_add_u64 v[68:69], v[4:5], 0, s[0:1]
	s_and_saveexec_b64 s[4:5], vcc
	global_load_dword v82, v[76:77], off
	s_or_b64 exec, exec, s[4:5]
	global_load_dwordx4 v[128:131], v[68:69], off
	global_load_dwordx4 v[132:135], v[68:69], off offset:1024
	global_load_dwordx4 v[136:139], v[68:69], off offset:2048
	global_load_dwordx4 v[140:143], v[68:69], off offset:3072
	s_add_i32 s12, s12, 1
	s_add_i32 s13, s13, s2
	s_cmp_lt_i32 s13, 0x8000
	s_cbranch_scc0 .Lmy_J_issued
	v_mov_b32_e32 v83, 0
	s_lshl_b32 s0, s13, 6
	v_lshl_add_u64 v[78:79], v[0:1], 0, s[0:1]
	s_lshl_b32 s0, s13, 12
	v_lshl_add_u64 v[70:71], v[4:5], 0, s[0:1]
	s_and_saveexec_b64 s[4:5], vcc
	global_load_dword v83, v[78:79], off
	s_or_b64 exec, exec, s[4:5]
	global_load_dwordx4 v[144:147], v[70:71], off
	global_load_dwordx4 v[148:151], v[70:71], off offset:1024
	global_load_dwordx4 v[152:155], v[70:71], off offset:2048
	global_load_dwordx4 v[156:159], v[70:71], off offset:3072
	s_add_i32 s12, s12, 1
	s_add_i32 s13, s13, s2
.Lmy_J_issued:
	s_waitcnt vmcnt(0)
	ds_bpermute_b32 v92, v6, v80
	ds_bpermute_b32 v93, v6, v81
	ds_bpermute_b32 v94, v6, v82
	ds_bpermute_b32 v95, v6, v83
	s_waitcnt lgkmcnt(0)
	v_add_f32_e32 v80, v80, v92
	v_add_f32_e32 v81, v81, v93
	v_add_f32_e32 v82, v82, v94
	v_add_f32_e32 v83, v83, v95
	ds_bpermute_b32 v92, v7, v80
	ds_bpermute_b32 v93, v7, v81
	ds_bpermute_b32 v94, v7, v82
	ds_bpermute_b32 v95, v7, v83
	s_waitcnt lgkmcnt(0)
	v_add_f32_e32 v80, v80, v92
	v_add_f32_e32 v81, v81, v93
	v_add_f32_e32 v82, v82, v94
	v_add_f32_e32 v83, v83, v95
	ds_bpermute_b32 v92, v8, v80
	ds_bpermute_b32 v93, v8, v81
	ds_bpermute_b32 v94, v8, v82
	ds_bpermute_b32 v95, v8, v83
	s_waitcnt lgkmcnt(0)
	v_add_f32_e32 v80, v80, v92
	v_add_f32_e32 v81, v81, v93
	v_add_f32_e32 v82, v82, v94
	v_add_f32_e32 v83, v83, v95
	ds_bpermute_b32 v92, v9, v80
	ds_bpermute_b32 v93, v9, v81
	ds_bpermute_b32 v94, v9, v82
	ds_bpermute_b32 v95, v9, v83
	s_waitcnt lgkmcnt(0)
	v_add_f32_e32 v80, v80, v92
	v_add_f32_e32 v81, v81, v93
	v_add_f32_e32 v82, v82, v94
	v_add_f32_e32 v83, v83, v95
	ds_bpermute_b32 v92, v10, v80
	ds_bpermute_b32 v93, v10, v81
	ds_bpermute_b32 v94, v10, v82
	ds_bpermute_b32 v95, v10, v83
	s_waitcnt lgkmcnt(0)
	v_add_f32_e32 v80, v80, v92
	v_add_f32_e32 v81, v81, v93
	v_add_f32_e32 v82, v82, v94
	v_add_f32_e32 v83, v83, v95
	ds_bpermute_b32 v92, v11, v80
	ds_bpermute_b32 v93, v11, v81
	ds_bpermute_b32 v94, v11, v82
	ds_bpermute_b32 v95, v11, v83
	s_waitcnt lgkmcnt(0)
; DI void phaseJ(int wv0, PP p) {
;     ...
;   for (int row = blockIdx.x * 8 + wv0; row < T_; row += gridDim.x * 8) {
;     float t = (lane < 16) ? SS2[(size_t)row * 16 + lane] : 0.f;
;     t = wave_sum(t);
;     const float rinv = rsqrtf(t * (1.f / 1024.f) + 1e-6f);
;     float4* xr = (float4*)(p->out + (size_t)row * 1024);
; #pragma unroll
;     for (int r = 0; r < 4; ++r) {
;       float4 v = xr[lane + 64 * r];
;       const float4 g = ((const float4*)p->g3)[lane + 64 * r];
;       v.x *= rinv * g.x; v.y *= rinv * g.y; v.z *= rinv * g.z; v.w *= rinv * g.w;
;       xr[lane + 64 * r] = v;
;     }
;   }
	v_add_f32_e32 v80, v80, v92
	v_add_f32_e32 v81, v81, v93
	v_add_f32_e32 v82, v82, v94
	v_add_f32_e32 v83, v83, v95
	v_fmamk_f32 v80, v80, 0x3a800000, v12
	v_fmamk_f32 v81, v81, 0x3a800000, v12
	v_fmamk_f32 v82, v82, 0x3a800000, v12
	v_fmamk_f32 v83, v83, 0x3a800000, v12
	v_mul_f32_e32 v92, 0x4b800000, v80
	v_cmp_gt_f32_e64 s[0:1], s3, v80
	s_nop 1
	v_cndmask_b32_e64 v80, v80, v92, s[0:1]
	v_rsq_f32_e32 v80, v80
	s_nop 0
	v_mul_f32_e32 v92, 0x45800000, v80
	v_cndmask_b32_e64 v84, v80, v92, s[0:1]
	v_mul_f32_e32 v92, 0x4b800000, v81
	v_cmp_gt_f32_e64 s[0:1], s3, v81
	s_nop 1
	v_cndmask_b32_e64 v81, v81, v92, s[0:1]
	v_rsq_f32_e32 v81, v81
	s_nop 0
	v_mul_f32_e32 v92, 0x45800000, v81
	v_cndmask_b32_e64 v86, v81, v92, s[0:1]
	v_mul_f32_e32 v92, 0x4b800000, v82
	v_cmp_gt_f32_e64 s[0:1], s3, v82
	s_nop 1
	v_cndmask_b32_e64 v82, v82, v92, s[0:1]
	v_rsq_f32_e32 v82, v82
	s_nop 0
	v_mul_f32_e32 v92, 0x45800000, v82
	v_cndmask_b32_e64 v88, v82, v92, s[0:1]
	v_mul_f32_e32 v92, 0x4b800000, v83
	v_cmp_gt_f32_e64 s[0:1], s3, v83
	s_nop 1
	v_cndmask_b32_e64 v83, v83, v92, s[0:1]
	v_rsq_f32_e32 v83, v83
	s_nop 0
	v_mul_f32_e32 v92, 0x45800000, v83
	v_cndmask_b32_e64 v90, v83, v92, s[0:1]
	v_pk_mul_f32 v[16:17], v[32:33], v[84:85] op_sel_hi:[1,0]
	v_pk_mul_f32 v[18:19], v[34:35], v[84:85] op_sel_hi:[1,0]
	v_pk_mul_f32 v[96:97], v[96:97], v[16:17]
	v_pk_mul_f32 v[98:99], v[98:99], v[18:19]
	global_store_dwordx4 v[64:65], v[96:99], off
	v_pk_mul_f32 v[16:17], v[84:85], v[36:37] op_sel_hi:[0,1]
	v_pk_mul_f32 v[18:19], v[84:85], v[38:39] op_sel_hi:[0,1]
	v_pk_mul_f32 v[100:101], v[100:101], v[16:17]
	v_pk_mul_f32 v[102:103], v[102:103], v[18:19]
	global_store_dwordx4 v[64:65], v[100:103], off offset:1024
	v_pk_mul_f32 v[16:17], v[84:85], v[40:41] op_sel_hi:[0,1]
	v_pk_mul_f32 v[18:19], v[84:85], v[42:43] op_sel_hi:[0,1]
	v_pk_mul_f32 v[104:105], v[104:105], v[16:17]
	v_pk_mul_f32 v[106:107], v[106:107], v[18:19]
	global_store_dwordx4 v[64:65], v[104:107], off offset:2048
	v_pk_mul_f32 v[16:17], v[84:85], v[44:45] op_sel_hi:[0,1]
	v_pk_mul_f32 v[18:19], v[84:85], v[46:47] op_sel_hi:[0,1]
	v_pk_mul_f32 v[108:109], v[108:109], v[16:17]
	v_pk_mul_f32 v[110:111], v[110:111], v[18:19]
	global_store_dwordx4 v[64:65], v[108:111], off offset:3072
	s_cmp_gt_u32 s12, 1
	s_cbranch_scc0 .Lmy_J_stored
	v_pk_mul_f32 v[16:17], v[32:33], v[86:87] op_sel_hi:[1,0]
	v_pk_mul_f32 v[18:19], v[34:35], v[86:87] op_sel_hi:[1,0]
	v_pk_mul_f32 v[112:113], v[112:113], v[16:17]
	v_pk_mul_f32 v[114:115], v[114:115], v[18:19]
	global_store_dwordx4 v[66:67], v[112:115], off
	v_pk_mul_f32 v[16:17], v[86:87], v[36:37] op_sel_hi:[0,1]
	v_pk_mul_f32 v[18:19], v[86:87], v[38:39] op_sel_hi:[0,1]
	v_pk_mul_f32 v[116:117], v[116:117], v[16:17]
	v_pk_mul_f32 v[118:119], v[118:119], v[18:19]
	global_store_dwordx4 v[66:67], v[116:119], off offset:1024
	v_pk_mul_f32 v[16:17], v[86:87], v[40:41] op_sel_hi:[0,1]
	v_pk_mul_f32 v[18:19], v[86:87], v[42:43] op_sel_hi:[0,1]
	v_pk_mul_f32 v[120:121], v[120:121], v[16:17]
	v_pk_mul_f32 v[122:123], v[122:123], v[18:19]
	global_store_dwordx4 v[66:67], v[120:123], off offset:2048
	v_pk_mul_f32 v[16:17], v[86:87], v[44:45] op_sel_hi:[0,1]
	v_pk_mul_f32 v[18:19], v[86:87], v[46:47] op_sel_hi:[0,1]
	v_pk_mul_f32 v[124:125], v[124:125], v[16:17]
	v_pk_mul_f32 v[126:127], v[126:127], v[18:19]
	global_store_dwordx4 v[66:67], v[124:127], off offset:3072
	s_cmp_gt_u32 s12, 2
	s_cbranch_scc0 .Lmy_J_stored
	v_pk_mul_f32 v[16:17], v[32:33], v[88:89] op_sel_hi:[1,0]
	v_pk_mul_f32 v[18:19], v[34:35], v[88:89] op_sel_hi:[1,0]
	v_pk_mul_f32 v[128:129], v[128:129], v[16:17]
	v_pk_mul_f32 v[130:131], v[130:131], v[18:19]
	global_store_dwordx4 v[68:69], v[128:131], off
	v_pk_mul_f32 v[16:17], v[88:89], v[36:37] op_sel_hi:[0,1]
	v_pk_mul_f32 v[18:19], v[88:89], v[38:39] op_sel_hi:[0,1]
	v_pk_mul_f32 v[132:133], v[132:133], v[16:17]
	v_pk_mul_f32 v[134:135], v[134:135], v[18:19]
	global_store_dwordx4 v[68:69], v[132:135], off offset:1024
	v_pk_mul_f32 v[16:17], v[88:89], v[40:41] op_sel_hi:[0,1]
	v_pk_mul_f32 v[18:19], v[88:89], v[42:43] op_sel_hi:[0,1]
	v_pk_mul_f32 v[136:137], v[136:137], v[16:17]
	v_pk_mul_f32 v[138:139], v[138:139], v[18:19]
	global_store_dwordx4 v[68:69], v[136:139], off offset:2048
	v_pk_mul_f32 v[16:17], v[88:89], v[44:45] op_sel_hi:[0,1]
	v_pk_mul_f32 v[18:19], v[88:89], v[46:47] op_sel_hi:[0,1]
	v_pk_mul_f32 v[140:141], v[140:141], v[16:17]
	v_pk_mul_f32 v[142:143], v[142:143], v[18:19]
	global_store_dwordx4 v[68:69], v[140:143], off offset:3072
	s_cmp_gt_u32 s12, 3
	s_cbranch_scc0 .Lmy_J_stored
	v_pk_mul_f32 v[16:17], v[32:33], v[90:91] op_sel_hi:[1,0]
	v_pk_mul_f32 v[18:19], v[34:35], v[90:91] op_sel_hi:[1,0]
	v_pk_mul_f32 v[144:145], v[144:145], v[16:17]
	v_pk_mul_f32 v[146:147], v[146:147], v[18:19]
	global_store_dwordx4 v[70:71], v[144:147], off
	v_pk_mul_f32 v[16:17], v[90:91], v[36:37] op_sel_hi:[0,1]
	v_pk_mul_f32 v[18:19], v[90:91], v[38:39] op_sel_hi:[0,1]
	v_pk_mul_f32 v[148:149], v[148:149], v[16:17]
	v_pk_mul_f32 v[150:151], v[150:151], v[18:19]
	global_store_dwordx4 v[70:71], v[148:151], off offset:1024
	v_pk_mul_f32 v[16:17], v[90:91], v[40:41] op_sel_hi:[0,1]
	v_pk_mul_f32 v[18:19], v[90:91], v[42:43] op_sel_hi:[0,1]
	v_pk_mul_f32 v[152:153], v[152:153], v[16:17]
	v_pk_mul_f32 v[154:155], v[154:155], v[18:19]
	global_store_dwordx4 v[70:71], v[152:155], off offset:2048
	v_pk_mul_f32 v[16:17], v[90:91], v[44:45] op_sel_hi:[0,1]
	v_pk_mul_f32 v[18:19], v[90:91], v[46:47] op_sel_hi:[0,1]
	v_pk_mul_f32 v[156:157], v[156:157], v[16:17]
	v_pk_mul_f32 v[158:159], v[158:159], v[18:19]
	global_store_dwordx4 v[70:71], v[156:159], off offset:3072
.Lmy_J_stored:
	s_mov_b32 s10, s13
	s_cmp_lt_i32 s10, 0x8000
	s_cbranch_scc1 .Lmy_J_loop
